# remaining six weight-transpose load loops fully unrolled: all 32/64 loads of an item in flight before first wait
# speedup vs baseline: 1.0045x; 1.0018x over previous
; #define LAS __attribute__((address_space(3)))
; __device__ __forceinline__ unsigned cvtpk(float lo, float hi) { f32x2 v = {lo, hi}; bf16x2_t b = __builtin_convertvector(v, bf16x2_t); return __builtin_bit_cast(unsigned, b); }
; __device__ __forceinline__ void transpose_item(const float* W, int K, int N, bf16_t* WT, const float* gain, int mode, LAS float* scr, int item, int lane) {
;     ...
; #pragma unroll 8
;     for (int i = 0; i < 32; ++i) { const int kk = 2 * i + (lane >> 5); float w = __builtin_nontemporal_load(W + (size_t)(k0 + kk) * N + n0 + (lane & 31)); if (gain) w *= gain[k0 + kk]; scr[kk * 33 + (lane & 31)] = w; }
;     int d0 = n0;
;     if (mode == 1) { const int j = n0 < DFF ? n0 : n0 - DFF; d0 = 256 * (j >> 7) + (j & 127) + (n0 < DFF ? 0 : 128); }
;     const int c = lane & 7;
; #pragma unroll
;     for (int j = 0; j < 4; ++j) { const int n = (lane >> 3) + 8 * j; const LAS float* s = scr + (8 * c) * 33 + n;
;         u32x4 o; o.x = cvtpk(s[0 * 33], s[1 * 33]); o.y = cvtpk(s[2 * 33], s[3 * 33]); o.z = cvtpk(s[4 * 33], s[5 * 33]); o.w = cvtpk(s[6 * 33], s[7 * 33]);
;         *(u32x4*)(WT + (size_t)(d0 + n) * K + k0 + 8 * c) = o; }
.LBB0_312:
	v_lshl_add_u64 v[20:21], v[16:17], 0, s[2:3]
	v_lshl_add_u64 v[22:23], v[14:15], 0, s[2:3]
	v_lshl_add_u64 v[24:25], v[12:13], 0, s[2:3]
	v_lshl_add_u64 v[26:27], v[10:11], 0, s[2:3]
	v_lshl_add_u64 v[28:29], v[8:9], 0, s[2:3]
	v_lshl_add_u64 v[30:31], v[6:7], 0, s[2:3]
	v_lshl_add_u64 v[32:33], v[4:5], 0, s[2:3]
	s_waitcnt vmcnt(0)
	v_lshl_add_u64 v[34:35], v[2:3], 0, s[2:3]
	global_load_dword v100, v[20:21], off nt
	s_nop 0
	global_load_dword v101, v[22:23], off nt
	global_load_dword v102, v[24:25], off nt
	s_nop 0
	global_load_dword v103, v[26:27], off nt
	global_load_dword v104, v[28:29], off nt
	global_load_dword v105, v[30:31], off nt
	global_load_dword v106, v[32:33], off nt
	s_nop 0
	global_load_dword v107, v[34:35], off nt
	s_add_u32 s2, s2, 0x10000
	s_addc_u32 s3, s3, 0
	v_lshl_add_u64 v[20:21], v[16:17], 0, s[2:3]
	v_lshl_add_u64 v[22:23], v[14:15], 0, s[2:3]
	v_lshl_add_u64 v[24:25], v[12:13], 0, s[2:3]
	v_lshl_add_u64 v[26:27], v[10:11], 0, s[2:3]
	v_lshl_add_u64 v[28:29], v[8:9], 0, s[2:3]
	v_lshl_add_u64 v[30:31], v[6:7], 0, s[2:3]
	v_lshl_add_u64 v[32:33], v[4:5], 0, s[2:3]
	v_lshl_add_u64 v[34:35], v[2:3], 0, s[2:3]
	global_load_dword v116, v[20:21], off nt
	s_nop 0
	global_load_dword v117, v[22:23], off nt
	global_load_dword v118, v[24:25], off nt
	s_nop 0
	global_load_dword v119, v[26:27], off nt
	global_load_dword v120, v[28:29], off nt
	global_load_dword v121, v[30:31], off nt
	global_load_dword v122, v[32:33], off nt
	s_nop 0
	global_load_dword v123, v[34:35], off nt
	s_add_u32 s2, s2, 0x10000
	s_addc_u32 s3, s3, 0
	v_lshl_add_u64 v[20:21], v[16:17], 0, s[2:3]
	v_lshl_add_u64 v[22:23], v[14:15], 0, s[2:3]
	v_lshl_add_u64 v[24:25], v[12:13], 0, s[2:3]
	v_lshl_add_u64 v[26:27], v[10:11], 0, s[2:3]
	v_lshl_add_u64 v[28:29], v[8:9], 0, s[2:3]
	v_lshl_add_u64 v[30:31], v[6:7], 0, s[2:3]
	v_lshl_add_u64 v[32:33], v[4:5], 0, s[2:3]
	v_lshl_add_u64 v[34:35], v[2:3], 0, s[2:3]
	global_load_dword v132, v[20:21], off nt
	s_nop 0
	global_load_dword v133, v[22:23], off nt
	global_load_dword v134, v[24:25], off nt
	s_nop 0
	global_load_dword v135, v[26:27], off nt
	global_load_dword v136, v[28:29], off nt
	global_load_dword v137, v[30:31], off nt
	global_load_dword v138, v[32:33], off nt
	s_nop 0
	global_load_dword v139, v[34:35], off nt
	s_add_u32 s2, s2, 0x10000
	s_addc_u32 s3, s3, 0
	v_lshl_add_u64 v[20:21], v[16:17], 0, s[2:3]
	v_lshl_add_u64 v[22:23], v[14:15], 0, s[2:3]
	v_lshl_add_u64 v[24:25], v[12:13], 0, s[2:3]
	v_lshl_add_u64 v[26:27], v[10:11], 0, s[2:3]
	v_lshl_add_u64 v[28:29], v[8:9], 0, s[2:3]
	v_lshl_add_u64 v[30:31], v[6:7], 0, s[2:3]
	v_lshl_add_u64 v[32:33], v[4:5], 0, s[2:3]
	v_lshl_add_u64 v[34:35], v[2:3], 0, s[2:3]
	global_load_dword v148, v[20:21], off nt
	s_nop 0
	global_load_dword v149, v[22:23], off nt
	global_load_dword v150, v[24:25], off nt
	s_nop 0
	global_load_dword v151, v[26:27], off nt
	global_load_dword v152, v[28:29], off nt
	global_load_dword v153, v[30:31], off nt
	global_load_dword v154, v[32:33], off nt
	s_nop 0
	global_load_dword v155, v[34:35], off nt
	s_add_u32 s2, s2, 0x10000
	s_addc_u32 s3, s3, 0
	v_add_u32_e32 v27, 0x400, v19
	s_waitcnt vmcnt(30)
	ds_write2_b32 v19, v100, v101 offset1:66
	s_waitcnt vmcnt(28)
	ds_write2_b32 v19, v102, v103 offset0:132 offset1:198
	s_waitcnt vmcnt(26)
	ds_write2_b32 v27, v104, v105 offset0:8 offset1:74
	s_waitcnt vmcnt(24)
	ds_write2_b32 v27, v106, v107 offset0:140 offset1:206
	v_add_u32_e32 v19, 0x840, v19
	v_add_u32_e32 v27, 0x400, v19
	s_waitcnt vmcnt(22)
	ds_write2_b32 v19, v116, v117 offset1:66
	s_waitcnt vmcnt(20)
	ds_write2_b32 v19, v118, v119 offset0:132 offset1:198
	s_waitcnt vmcnt(18)
	ds_write2_b32 v27, v120, v121 offset0:8 offset1:74
	s_waitcnt vmcnt(16)
	ds_write2_b32 v27, v122, v123 offset0:140 offset1:206
	v_add_u32_e32 v19, 0x840, v19
	v_add_u32_e32 v27, 0x400, v19
	s_waitcnt vmcnt(14)
	ds_write2_b32 v19, v132, v133 offset1:66
	s_waitcnt vmcnt(12)
	ds_write2_b32 v19, v134, v135 offset0:132 offset1:198
	s_waitcnt vmcnt(10)
	ds_write2_b32 v27, v136, v137 offset0:8 offset1:74
	s_waitcnt vmcnt(8)
	ds_write2_b32 v27, v138, v139 offset0:140 offset1:206
	v_add_u32_e32 v19, 0x840, v19
	v_add_u32_e32 v27, 0x400, v19
	s_waitcnt vmcnt(6)
	ds_write2_b32 v19, v148, v149 offset1:66
	s_waitcnt vmcnt(4)
	ds_write2_b32 v19, v150, v151 offset0:132 offset1:198
	s_waitcnt vmcnt(2)
	ds_write2_b32 v27, v152, v153 offset0:8 offset1:74
	s_waitcnt vmcnt(0)
	ds_write2_b32 v27, v154, v155 offset0:140 offset1:206
	v_add_u32_e32 v19, 0x840, v19
	v_lshlrev_b32_e32 v0, 3, v18
	v_ashrrev_i32_e32 v24, 3, v18
	v_and_b32_e32 v0, 56, v0
	s_lshl_b32 s2, s36, 1
	v_mul_u32_u24_e32 v2, 0x84, v0
	v_lshlrev_b32_e32 v3, 2, v24
	v_readlane_b32 s11, v254, 15
	s_add_i32 s2, s2, 0x1ac00
	s_and_b32 s2, s2, 0x1ffc0
	v_add3_u32 v26, s11, v2, v3
	s_lshl_b32 s3, s36, 5
	ds_read2_b32 v[6:7], v26 offset0:33 offset1:41
	ds_read2_b32 v[8:9], v26 offset1:8
	ds_read2_b32 v[10:11], v26 offset0:66 offset1:74
	ds_read2_b32 v[12:13], v26 offset0:99 offset1:107
	ds_read2_b32 v[14:15], v26 offset0:132 offset1:140
	ds_read2_b32 v[16:17], v26 offset0:165 offset1:173
	ds_read2_b32 v[18:19], v26 offset0:198 offset1:206
	ds_read2_b32 v[20:21], v26 offset0:231 offset1:239
	s_and_b32 s10, s3, 0x3e0
	s_lshl_b32 s2, s2, 1
	s_add_u32 s2, s0, s2
	s_addc_u32 s3, s1, 0
	v_lshlrev_b32_e32 v0, 1, v0
	v_lshl_add_u64 v[22:23], s[2:3], 0, v[0:1]
	v_add_u32_e32 v0, s10, v24
	s_movk_i32 s10, 0x1600
	s_waitcnt lgkmcnt(6)
	v_cvt_pk_bf16_f32 v2, v8, v6
	s_waitcnt lgkmcnt(4)
	v_cvt_pk_bf16_f32 v3, v10, v12
	s_waitcnt lgkmcnt(2)
	v_cvt_pk_bf16_f32 v4, v14, v16
	s_waitcnt lgkmcnt(0)
	v_cvt_pk_bf16_f32 v5, v18, v20
	v_mad_i64_i32 v[24:25], s[2:3], v0, s10, v[22:23]
	global_store_dwordx4 v[24:25], v[2:5], off
	v_add_u32_e32 v6, 8, v0
	s_nop 0
	v_cvt_pk_bf16_f32 v2, v9, v7
	v_cvt_pk_bf16_f32 v3, v11, v13
	v_cvt_pk_bf16_f32 v4, v15, v17
	v_cvt_pk_bf16_f32 v5, v19, v21
	ds_read2_b32 v[8:9], v26 offset0:49 offset1:57
	ds_read2_b32 v[10:11], v26 offset0:16 offset1:24
	ds_read2_b32 v[12:13], v26 offset0:82 offset1:90
	ds_read2_b32 v[14:15], v26 offset0:115 offset1:123
	ds_read2_b32 v[16:17], v26 offset0:148 offset1:156
	ds_read2_b32 v[18:19], v26 offset0:181 offset1:189
	ds_read2_b32 v[20:21], v26 offset0:214 offset1:222
	ds_read2_b32 v[24:25], v26 offset0:247 offset1:255
	v_mad_i64_i32 v[6:7], s[2:3], v6, s10, v[22:23]
	global_store_dwordx4 v[6:7], v[2:5], off
	v_add_u32_e32 v6, 16, v0
	v_mad_i64_i32 v[6:7], s[2:3], v6, s10, v[22:23]
	s_waitcnt lgkmcnt(6)
	v_cvt_pk_bf16_f32 v2, v10, v8
	s_waitcnt lgkmcnt(4)
	v_cvt_pk_bf16_f32 v3, v12, v14
	s_waitcnt lgkmcnt(2)
	v_cvt_pk_bf16_f32 v4, v16, v18
	s_waitcnt lgkmcnt(0)
	v_cvt_pk_bf16_f32 v5, v20, v24
	v_add_u32_e32 v0, 24, v0
	global_store_dwordx4 v[6:7], v[2:5], off
	v_mad_i64_i32 v[6:7], s[2:3], v0, s10, v[22:23]
	s_nop 0
	v_cvt_pk_bf16_f32 v2, v11, v9
	v_cvt_pk_bf16_f32 v3, v13, v15
	v_cvt_pk_bf16_f32 v4, v17, v19
	v_cvt_pk_bf16_f32 v5, v21, v25
	global_store_dwordx4 v[6:7], v[2:5], off
	s_mov_b64 s[2:3], 0

; #define LAS __attribute__((address_space(3)))
; __device__ __forceinline__ unsigned cvtpk(float lo, float hi) { f32x2 v = {lo, hi}; bf16x2_t b = __builtin_convertvector(v, bf16x2_t); return __builtin_bit_cast(unsigned, b); }
; __device__ __forceinline__ void transpose_item(const float* W, int K, int N, bf16_t* WT, const float* gain, int mode, LAS float* scr, int item, int lane) {
;     ...
; #pragma unroll 8
;     for (int i = 0; i < 32; ++i) { const int kk = 2 * i + (lane >> 5); float w = __builtin_nontemporal_load(W + (size_t)(k0 + kk) * N + n0 + (lane & 31)); if (gain) w *= gain[k0 + kk]; scr[kk * 33 + (lane & 31)] = w; }
;     int d0 = n0;
;     if (mode == 1) { const int j = n0 < DFF ? n0 : n0 - DFF; d0 = 256 * (j >> 7) + (j & 127) + (n0 < DFF ? 0 : 128); }
;     const int c = lane & 7;
; #pragma unroll
;     for (int j = 0; j < 4; ++j) { const int n = (lane >> 3) + 8 * j; const LAS float* s = scr + (8 * c) * 33 + n;
;         u32x4 o; o.x = cvtpk(s[0 * 33], s[1 * 33]); o.y = cvtpk(s[2 * 33], s[3 * 33]); o.z = cvtpk(s[4 * 33], s[5 * 33]); o.w = cvtpk(s[6 * 33], s[7 * 33]);
;         *(u32x4*)(WT + (size_t)(d0 + n) * K + k0 + 8 * c) = o; }
.LBB0_316:
	v_lshl_add_u64 v[20:21], v[16:17], 0, s[2:3]
	v_lshl_add_u64 v[22:23], v[14:15], 0, s[2:3]
	v_lshl_add_u64 v[24:25], v[12:13], 0, s[2:3]
	v_lshl_add_u64 v[26:27], v[10:11], 0, s[2:3]
	v_lshl_add_u64 v[28:29], v[8:9], 0, s[2:3]
	v_lshl_add_u64 v[30:31], v[6:7], 0, s[2:3]
	v_lshl_add_u64 v[32:33], v[4:5], 0, s[2:3]
	s_waitcnt vmcnt(0)
	v_lshl_add_u64 v[34:35], v[2:3], 0, s[2:3]
	global_load_dword v100, v[20:21], off nt
	s_nop 0
	global_load_dword v101, v[22:23], off nt
	global_load_dword v102, v[24:25], off nt
	s_nop 0
	global_load_dword v103, v[26:27], off nt
	global_load_dword v104, v[28:29], off nt
	global_load_dword v105, v[30:31], off nt
	global_load_dword v106, v[32:33], off nt
	s_nop 0
	global_load_dword v107, v[34:35], off nt
	s_add_u32 s2, s2, 0x10000
	s_addc_u32 s3, s3, 0
	v_lshl_add_u64 v[20:21], v[16:17], 0, s[2:3]
	v_lshl_add_u64 v[22:23], v[14:15], 0, s[2:3]
	v_lshl_add_u64 v[24:25], v[12:13], 0, s[2:3]
	v_lshl_add_u64 v[26:27], v[10:11], 0, s[2:3]
	v_lshl_add_u64 v[28:29], v[8:9], 0, s[2:3]
	v_lshl_add_u64 v[30:31], v[6:7], 0, s[2:3]
	v_lshl_add_u64 v[32:33], v[4:5], 0, s[2:3]
	v_lshl_add_u64 v[34:35], v[2:3], 0, s[2:3]
	global_load_dword v116, v[20:21], off nt
	s_nop 0
	global_load_dword v117, v[22:23], off nt
	global_load_dword v118, v[24:25], off nt
	s_nop 0
	global_load_dword v119, v[26:27], off nt
	global_load_dword v120, v[28:29], off nt
	global_load_dword v121, v[30:31], off nt
	global_load_dword v122, v[32:33], off nt
	s_nop 0
	global_load_dword v123, v[34:35], off nt
	s_add_u32 s2, s2, 0x10000
	s_addc_u32 s3, s3, 0
	v_lshl_add_u64 v[20:21], v[16:17], 0, s[2:3]
	v_lshl_add_u64 v[22:23], v[14:15], 0, s[2:3]
	v_lshl_add_u64 v[24:25], v[12:13], 0, s[2:3]
	v_lshl_add_u64 v[26:27], v[10:11], 0, s[2:3]
	v_lshl_add_u64 v[28:29], v[8:9], 0, s[2:3]
	v_lshl_add_u64 v[30:31], v[6:7], 0, s[2:3]
	v_lshl_add_u64 v[32:33], v[4:5], 0, s[2:3]
	v_lshl_add_u64 v[34:35], v[2:3], 0, s[2:3]
	global_load_dword v132, v[20:21], off nt
	s_nop 0
	global_load_dword v133, v[22:23], off nt
	global_load_dword v134, v[24:25], off nt
	s_nop 0
	global_load_dword v135, v[26:27], off nt
	global_load_dword v136, v[28:29], off nt
	global_load_dword v137, v[30:31], off nt
	global_load_dword v138, v[32:33], off nt
	s_nop 0
	global_load_dword v139, v[34:35], off nt
	s_add_u32 s2, s2, 0x10000
	s_addc_u32 s3, s3, 0
	v_lshl_add_u64 v[20:21], v[16:17], 0, s[2:3]
	v_lshl_add_u64 v[22:23], v[14:15], 0, s[2:3]
	v_lshl_add_u64 v[24:25], v[12:13], 0, s[2:3]
	v_lshl_add_u64 v[26:27], v[10:11], 0, s[2:3]
	v_lshl_add_u64 v[28:29], v[8:9], 0, s[2:3]
	v_lshl_add_u64 v[30:31], v[6:7], 0, s[2:3]
	v_lshl_add_u64 v[32:33], v[4:5], 0, s[2:3]
	v_lshl_add_u64 v[34:35], v[2:3], 0, s[2:3]
	global_load_dword v148, v[20:21], off nt
	s_nop 0
	global_load_dword v149, v[22:23], off nt
	global_load_dword v150, v[24:25], off nt
	s_nop 0
	global_load_dword v151, v[26:27], off nt
	global_load_dword v152, v[28:29], off nt
	global_load_dword v153, v[30:31], off nt
	global_load_dword v154, v[32:33], off nt
	s_nop 0
	global_load_dword v155, v[34:35], off nt
	s_add_u32 s2, s2, 0x10000
	s_addc_u32 s3, s3, 0
	v_add_u32_e32 v27, 0x400, v19
	s_waitcnt vmcnt(30)
	ds_write2_b32 v19, v100, v101 offset1:66
	s_waitcnt vmcnt(28)
	ds_write2_b32 v19, v102, v103 offset0:132 offset1:198
	s_waitcnt vmcnt(26)
	ds_write2_b32 v27, v104, v105 offset0:8 offset1:74
	s_waitcnt vmcnt(24)
	ds_write2_b32 v27, v106, v107 offset0:140 offset1:206
	v_add_u32_e32 v19, 0x840, v19
	v_add_u32_e32 v27, 0x400, v19
	s_waitcnt vmcnt(22)
	ds_write2_b32 v19, v116, v117 offset1:66
	s_waitcnt vmcnt(20)
	ds_write2_b32 v19, v118, v119 offset0:132 offset1:198
	s_waitcnt vmcnt(18)
	ds_write2_b32 v27, v120, v121 offset0:8 offset1:74
	s_waitcnt vmcnt(16)
	ds_write2_b32 v27, v122, v123 offset0:140 offset1:206
	v_add_u32_e32 v19, 0x840, v19
	v_add_u32_e32 v27, 0x400, v19
	s_waitcnt vmcnt(14)
	ds_write2_b32 v19, v132, v133 offset1:66
	s_waitcnt vmcnt(12)
	ds_write2_b32 v19, v134, v135 offset0:132 offset1:198
	s_waitcnt vmcnt(10)
	ds_write2_b32 v27, v136, v137 offset0:8 offset1:74
	s_waitcnt vmcnt(8)
	ds_write2_b32 v27, v138, v139 offset0:140 offset1:206
	v_add_u32_e32 v19, 0x840, v19
	v_add_u32_e32 v27, 0x400, v19
	s_waitcnt vmcnt(6)
	ds_write2_b32 v19, v148, v149 offset1:66
	s_waitcnt vmcnt(4)
	ds_write2_b32 v19, v150, v151 offset0:132 offset1:198
	s_waitcnt vmcnt(2)
	ds_write2_b32 v27, v152, v153 offset0:8 offset1:74
	s_waitcnt vmcnt(0)
	ds_write2_b32 v27, v154, v155 offset0:140 offset1:206
	v_add_u32_e32 v19, 0x840, v19
	v_lshlrev_b32_e32 v0, 3, v18
	v_ashrrev_i32_e32 v24, 3, v18
	v_and_b32_e32 v0, 56, v0
	s_lshl_b32 s2, s36, 1
	v_mul_u32_u24_e32 v2, 0x84, v0
	v_lshlrev_b32_e32 v3, 2, v24
	v_readlane_b32 s11, v254, 15
	s_add_i32 s2, s2, 0x1b700
	s_and_b32 s2, s2, 0x1ffc0
	v_add3_u32 v26, s11, v2, v3
	s_lshl_b32 s3, s36, 5
	ds_read2_b32 v[6:7], v26 offset0:33 offset1:41
	ds_read2_b32 v[8:9], v26 offset1:8
	ds_read2_b32 v[10:11], v26 offset0:66 offset1:74
	ds_read2_b32 v[12:13], v26 offset0:99 offset1:107
	ds_read2_b32 v[14:15], v26 offset0:132 offset1:140
	ds_read2_b32 v[16:17], v26 offset0:165 offset1:173
	ds_read2_b32 v[18:19], v26 offset0:198 offset1:206
	ds_read2_b32 v[20:21], v26 offset0:231 offset1:239
	s_and_b32 s10, s3, 0x3e0
	s_lshl_b32 s2, s2, 1
	s_add_u32 s2, s4, s2
	s_addc_u32 s3, s5, 0
	v_lshlrev_b32_e32 v0, 1, v0
	v_lshl_add_u64 v[22:23], s[2:3], 0, v[0:1]
	v_add_u32_e32 v0, s10, v24
	s_movk_i32 s10, 0x1600
	s_waitcnt lgkmcnt(6)
	v_cvt_pk_bf16_f32 v2, v8, v6
	s_waitcnt lgkmcnt(4)
	v_cvt_pk_bf16_f32 v3, v10, v12
	s_waitcnt lgkmcnt(2)
	v_cvt_pk_bf16_f32 v4, v14, v16
	s_waitcnt lgkmcnt(0)
	v_cvt_pk_bf16_f32 v5, v18, v20
	v_mad_i64_i32 v[24:25], s[2:3], v0, s10, v[22:23]
	global_store_dwordx4 v[24:25], v[2:5], off
	v_add_u32_e32 v6, 8, v0
	s_nop 0
	v_cvt_pk_bf16_f32 v2, v9, v7
	v_cvt_pk_bf16_f32 v3, v11, v13
	v_cvt_pk_bf16_f32 v4, v15, v17
	v_cvt_pk_bf16_f32 v5, v19, v21
	ds_read2_b32 v[8:9], v26 offset0:49 offset1:57
	ds_read2_b32 v[10:11], v26 offset0:16 offset1:24
	ds_read2_b32 v[12:13], v26 offset0:82 offset1:90
	ds_read2_b32 v[14:15], v26 offset0:115 offset1:123
	ds_read2_b32 v[16:17], v26 offset0:148 offset1:156
	ds_read2_b32 v[18:19], v26 offset0:181 offset1:189
	ds_read2_b32 v[20:21], v26 offset0:214 offset1:222
	ds_read2_b32 v[24:25], v26 offset0:247 offset1:255
	v_mad_i64_i32 v[6:7], s[2:3], v6, s10, v[22:23]
	global_store_dwordx4 v[6:7], v[2:5], off
	v_add_u32_e32 v6, 16, v0
	v_mad_i64_i32 v[6:7], s[2:3], v6, s10, v[22:23]
	s_waitcnt lgkmcnt(6)
	v_cvt_pk_bf16_f32 v2, v10, v8
	s_waitcnt lgkmcnt(4)
	v_cvt_pk_bf16_f32 v3, v12, v14
	s_waitcnt lgkmcnt(2)
	v_cvt_pk_bf16_f32 v4, v16, v18
	s_waitcnt lgkmcnt(0)
	v_cvt_pk_bf16_f32 v5, v20, v24
	v_add_u32_e32 v0, 24, v0
	global_store_dwordx4 v[6:7], v[2:5], off
	v_mad_i64_i32 v[6:7], s[2:3], v0, s10, v[22:23]
	s_nop 0
	v_cvt_pk_bf16_f32 v2, v11, v9
	v_cvt_pk_bf16_f32 v3, v13, v15
	v_cvt_pk_bf16_f32 v4, v17, v19
	v_cvt_pk_bf16_f32 v5, v21, v25
	global_store_dwordx4 v[6:7], v[2:5], off

; __device__ __forceinline__ void transpose_item(const float* W, int K, int N, bf16_t* WT, const float* gain, int mode, LAS float* scr, int item, int lane) {
;     ...
; #pragma unroll 8
;     for (int i = 0; i < 32; ++i) { const int kk = 2 * i + (lane >> 5); float w = __builtin_nontemporal_load(W + (size_t)(k0 + kk) * N + n0 + (lane & 31)); if (gain) w *= gain[k0 + kk]; scr[kk * 33 + (lane & 31)] = w; }
.LBB0_321:
	v_lshl_add_u64 v[36:37], v[30:31], 0, v[0:1]
	v_lshl_add_u64 v[38:39], v[32:33], 0, s[2:3]
	v_lshl_add_u64 v[40:41], v[28:29], 0, v[0:1]
	v_lshl_add_u64 v[42:43], v[26:27], 0, s[2:3]
	v_lshl_add_u64 v[44:45], v[24:25], 0, v[0:1]
	v_lshl_add_u64 v[46:47], v[22:23], 0, s[2:3]
	v_lshl_add_u64 v[48:49], v[20:21], 0, v[0:1]
	v_lshl_add_u64 v[50:51], v[18:19], 0, s[2:3]
	v_lshl_add_u64 v[52:53], v[16:17], 0, v[0:1]
	v_lshl_add_u64 v[54:55], v[14:15], 0, s[2:3]
	v_lshl_add_u64 v[56:57], v[12:13], 0, v[0:1]
	v_lshl_add_u64 v[58:59], v[10:11], 0, s[2:3]
	v_lshl_add_u64 v[60:61], v[8:9], 0, v[0:1]
	v_lshl_add_u64 v[62:63], v[6:7], 0, s[2:3]
	v_lshl_add_u64 v[64:65], v[4:5], 0, v[0:1]
	v_lshl_add_u64 v[66:67], v[2:3], 0, s[2:3]
	global_load_dword v100, v[36:37], off nt
	s_nop 0
	global_load_dword v101, v[38:39], off
	s_nop 0
	global_load_dword v102, v[40:41], off nt
	global_load_dword v103, v[42:43], off
	s_nop 0
	global_load_dword v104, v[44:45], off nt
	global_load_dword v105, v[46:47], off
	global_load_dword v106, v[48:49], off nt
	global_load_dword v107, v[50:51], off
	s_nop 0
	global_load_dword v108, v[52:53], off nt
	global_load_dword v109, v[54:55], off
	global_load_dword v110, v[56:57], off nt
	global_load_dword v111, v[58:59], off
	global_load_dword v112, v[60:61], off nt
	global_load_dword v113, v[62:63], off
	global_load_dword v114, v[64:65], off nt
	global_load_dword v115, v[66:67], off
	s_add_u32 s2, s2, 64
	s_addc_u32 s3, s3, 0
	v_lshl_add_u64 v[4:5], v[4:5], 0, s[38:39]
	v_lshl_add_u64 v[8:9], v[8:9], 0, s[38:39]
	v_lshl_add_u64 v[12:13], v[12:13], 0, s[38:39]
	v_lshl_add_u64 v[16:17], v[16:17], 0, s[38:39]
	v_lshl_add_u64 v[20:21], v[20:21], 0, s[38:39]
	v_lshl_add_u64 v[24:25], v[24:25], 0, s[38:39]
	v_lshl_add_u64 v[28:29], v[28:29], 0, s[38:39]
	v_lshl_add_u64 v[30:31], v[30:31], 0, s[38:39]
	v_lshl_add_u64 v[36:37], v[30:31], 0, v[0:1]
	v_lshl_add_u64 v[38:39], v[32:33], 0, s[2:3]
	v_lshl_add_u64 v[40:41], v[28:29], 0, v[0:1]
	v_lshl_add_u64 v[42:43], v[26:27], 0, s[2:3]
	v_lshl_add_u64 v[44:45], v[24:25], 0, v[0:1]
	v_lshl_add_u64 v[46:47], v[22:23], 0, s[2:3]
	v_lshl_add_u64 v[48:49], v[20:21], 0, v[0:1]
	v_lshl_add_u64 v[50:51], v[18:19], 0, s[2:3]
	v_lshl_add_u64 v[52:53], v[16:17], 0, v[0:1]
	v_lshl_add_u64 v[54:55], v[14:15], 0, s[2:3]
	v_lshl_add_u64 v[56:57], v[12:13], 0, v[0:1]
	v_lshl_add_u64 v[58:59], v[10:11], 0, s[2:3]
	v_lshl_add_u64 v[60:61], v[8:9], 0, v[0:1]
	v_lshl_add_u64 v[62:63], v[6:7], 0, s[2:3]
	v_lshl_add_u64 v[64:65], v[4:5], 0, v[0:1]
	v_lshl_add_u64 v[66:67], v[2:3], 0, s[2:3]
	global_load_dword v116, v[36:37], off nt
	s_nop 0
	global_load_dword v117, v[38:39], off
	s_nop 0
	global_load_dword v118, v[40:41], off nt
	global_load_dword v119, v[42:43], off
	s_nop 0
	global_load_dword v120, v[44:45], off nt
	global_load_dword v121, v[46:47], off
	global_load_dword v122, v[48:49], off nt
	global_load_dword v123, v[50:51], off
	s_nop 0
	global_load_dword v124, v[52:53], off nt
	global_load_dword v125, v[54:55], off
	global_load_dword v126, v[56:57], off nt
	global_load_dword v127, v[58:59], off
	global_load_dword v128, v[60:61], off nt
	global_load_dword v129, v[62:63], off
	global_load_dword v130, v[64:65], off nt
	global_load_dword v131, v[66:67], off
	s_add_u32 s2, s2, 64
	s_addc_u32 s3, s3, 0
	v_lshl_add_u64 v[4:5], v[4:5], 0, s[38:39]
	v_lshl_add_u64 v[8:9], v[8:9], 0, s[38:39]
	v_lshl_add_u64 v[12:13], v[12:13], 0, s[38:39]
	v_lshl_add_u64 v[16:17], v[16:17], 0, s[38:39]
	v_lshl_add_u64 v[20:21], v[20:21], 0, s[38:39]
	v_lshl_add_u64 v[24:25], v[24:25], 0, s[38:39]
	v_lshl_add_u64 v[28:29], v[28:29], 0, s[38:39]
	v_lshl_add_u64 v[30:31], v[30:31], 0, s[38:39]
	v_lshl_add_u64 v[36:37], v[30:31], 0, v[0:1]
	v_lshl_add_u64 v[38:39], v[32:33], 0, s[2:3]
	v_lshl_add_u64 v[40:41], v[28:29], 0, v[0:1]
	v_lshl_add_u64 v[42:43], v[26:27], 0, s[2:3]
	v_lshl_add_u64 v[44:45], v[24:25], 0, v[0:1]
	v_lshl_add_u64 v[46:47], v[22:23], 0, s[2:3]
	v_lshl_add_u64 v[48:49], v[20:21], 0, v[0:1]
	v_lshl_add_u64 v[50:51], v[18:19], 0, s[2:3]
	v_lshl_add_u64 v[52:53], v[16:17], 0, v[0:1]
	v_lshl_add_u64 v[54:55], v[14:15], 0, s[2:3]
	v_lshl_add_u64 v[56:57], v[12:13], 0, v[0:1]
	v_lshl_add_u64 v[58:59], v[10:11], 0, s[2:3]
	v_lshl_add_u64 v[60:61], v[8:9], 0, v[0:1]
	v_lshl_add_u64 v[62:63], v[6:7], 0, s[2:3]
	v_lshl_add_u64 v[64:65], v[4:5], 0, v[0:1]
	v_lshl_add_u64 v[66:67], v[2:3], 0, s[2:3]
	global_load_dword v132, v[36:37], off nt
	s_nop 0
	global_load_dword v133, v[38:39], off
	s_nop 0
	global_load_dword v134, v[40:41], off nt
	global_load_dword v135, v[42:43], off
	s_nop 0
	global_load_dword v136, v[44:45], off nt
	global_load_dword v137, v[46:47], off
	global_load_dword v138, v[48:49], off nt
	global_load_dword v139, v[50:51], off
	s_nop 0
	global_load_dword v140, v[52:53], off nt
	global_load_dword v141, v[54:55], off
	global_load_dword v142, v[56:57], off nt
	global_load_dword v143, v[58:59], off
	global_load_dword v144, v[60:61], off nt
	global_load_dword v145, v[62:63], off
	global_load_dword v146, v[64:65], off nt
	global_load_dword v147, v[66:67], off
	s_add_u32 s2, s2, 64
	s_addc_u32 s3, s3, 0
	v_lshl_add_u64 v[4:5], v[4:5], 0, s[38:39]
	v_lshl_add_u64 v[8:9], v[8:9], 0, s[38:39]
	v_lshl_add_u64 v[12:13], v[12:13], 0, s[38:39]
	v_lshl_add_u64 v[16:17], v[16:17], 0, s[38:39]
	v_lshl_add_u64 v[20:21], v[20:21], 0, s[38:39]
	v_lshl_add_u64 v[24:25], v[24:25], 0, s[38:39]
	v_lshl_add_u64 v[28:29], v[28:29], 0, s[38:39]
	v_lshl_add_u64 v[30:31], v[30:31], 0, s[38:39]
	v_lshl_add_u64 v[36:37], v[30:31], 0, v[0:1]
	v_lshl_add_u64 v[38:39], v[32:33], 0, s[2:3]
	v_lshl_add_u64 v[40:41], v[28:29], 0, v[0:1]
; __device__ __forceinline__ void transpose_item(const float* W, int K, int N, bf16_t* WT, const float* gain, int mode, LAS float* scr, int item, int lane) {
;     ...
; #pragma unroll 8
;     for (int i = 0; i < 32; ++i) { const int kk = 2 * i + (lane >> 5); float w = __builtin_nontemporal_load(W + (size_t)(k0 + kk) * N + n0 + (lane & 31)); if (gain) w *= gain[k0 + kk]; scr[kk * 33 + (lane & 31)] = w; }
	v_lshl_add_u64 v[42:43], v[26:27], 0, s[2:3]
	v_lshl_add_u64 v[44:45], v[24:25], 0, v[0:1]
	v_lshl_add_u64 v[46:47], v[22:23], 0, s[2:3]
	v_lshl_add_u64 v[48:49], v[20:21], 0, v[0:1]
	v_lshl_add_u64 v[50:51], v[18:19], 0, s[2:3]
	v_lshl_add_u64 v[52:53], v[16:17], 0, v[0:1]
	v_lshl_add_u64 v[54:55], v[14:15], 0, s[2:3]
	v_lshl_add_u64 v[56:57], v[12:13], 0, v[0:1]
	v_lshl_add_u64 v[58:59], v[10:11], 0, s[2:3]
	v_lshl_add_u64 v[60:61], v[8:9], 0, v[0:1]
	v_lshl_add_u64 v[62:63], v[6:7], 0, s[2:3]
	v_lshl_add_u64 v[64:65], v[4:5], 0, v[0:1]
	v_lshl_add_u64 v[66:67], v[2:3], 0, s[2:3]
	global_load_dword v148, v[36:37], off nt
	s_nop 0
	global_load_dword v149, v[38:39], off
	s_nop 0
	global_load_dword v150, v[40:41], off nt
	global_load_dword v151, v[42:43], off
	s_nop 0
	global_load_dword v152, v[44:45], off nt
	global_load_dword v153, v[46:47], off
	global_load_dword v154, v[48:49], off nt
	global_load_dword v155, v[50:51], off
	s_nop 0
	global_load_dword v156, v[52:53], off nt
	global_load_dword v157, v[54:55], off
	global_load_dword v158, v[56:57], off nt
	global_load_dword v159, v[58:59], off
	global_load_dword v160, v[60:61], off nt
	global_load_dword v161, v[62:63], off
	global_load_dword v162, v[64:65], off nt
	global_load_dword v163, v[66:67], off
	s_add_u32 s2, s2, 64
	s_addc_u32 s3, s3, 0
	v_lshl_add_u64 v[4:5], v[4:5], 0, s[38:39]
	v_lshl_add_u64 v[8:9], v[8:9], 0, s[38:39]
	v_lshl_add_u64 v[12:13], v[12:13], 0, s[38:39]
	v_lshl_add_u64 v[16:17], v[16:17], 0, s[38:39]
	v_lshl_add_u64 v[20:21], v[20:21], 0, s[38:39]
	v_lshl_add_u64 v[24:25], v[24:25], 0, s[38:39]
	v_lshl_add_u64 v[28:29], v[28:29], 0, s[38:39]
	v_lshl_add_u64 v[30:31], v[30:31], 0, s[38:39]
	v_add_u32_e32 v52, 0x400, v35
	s_waitcnt vmcnt(62)
	v_mul_f32_e32 v100, v100, v101
	s_waitcnt vmcnt(60)
	v_mul_f32_e32 v101, v102, v103
	s_waitcnt vmcnt(58)
	v_mul_f32_e32 v102, v104, v105
	s_waitcnt vmcnt(56)
	v_mul_f32_e32 v103, v106, v107
	s_waitcnt vmcnt(54)
	v_mul_f32_e32 v104, v108, v109
	s_waitcnt vmcnt(52)
	v_mul_f32_e32 v105, v110, v111
	s_waitcnt vmcnt(50)
	v_mul_f32_e32 v106, v112, v113
	s_waitcnt vmcnt(48)
	v_mul_f32_e32 v107, v114, v115
	ds_write2_b32 v35, v100, v101 offset1:66
	ds_write2_b32 v35, v102, v103 offset0:132 offset1:198
	ds_write2_b32 v52, v104, v105 offset0:8 offset1:74
	ds_write2_b32 v52, v106, v107 offset0:140 offset1:206
	v_add_u32_e32 v35, 0x840, v35
	v_add_u32_e32 v52, 0x400, v35
	s_waitcnt vmcnt(46)
	v_mul_f32_e32 v116, v116, v117
	s_waitcnt vmcnt(44)
	v_mul_f32_e32 v117, v118, v119
	s_waitcnt vmcnt(42)
	v_mul_f32_e32 v118, v120, v121
	s_waitcnt vmcnt(40)
	v_mul_f32_e32 v119, v122, v123
	s_waitcnt vmcnt(38)
	v_mul_f32_e32 v120, v124, v125
	s_waitcnt vmcnt(36)
	v_mul_f32_e32 v121, v126, v127
	s_waitcnt vmcnt(34)
	v_mul_f32_e32 v122, v128, v129
	s_waitcnt vmcnt(32)
	v_mul_f32_e32 v123, v130, v131
	ds_write2_b32 v35, v116, v117 offset1:66
	ds_write2_b32 v35, v118, v119 offset0:132 offset1:198
	ds_write2_b32 v52, v120, v121 offset0:8 offset1:74
	ds_write2_b32 v52, v122, v123 offset0:140 offset1:206
	v_add_u32_e32 v35, 0x840, v35
	v_add_u32_e32 v52, 0x400, v35
	s_waitcnt vmcnt(30)
	v_mul_f32_e32 v132, v132, v133
	s_waitcnt vmcnt(28)
	v_mul_f32_e32 v133, v134, v135
	s_waitcnt vmcnt(26)
	v_mul_f32_e32 v134, v136, v137
	s_waitcnt vmcnt(24)
	v_mul_f32_e32 v135, v138, v139
	s_waitcnt vmcnt(22)
	v_mul_f32_e32 v136, v140, v141
	s_waitcnt vmcnt(20)
	v_mul_f32_e32 v137, v142, v143
	s_waitcnt vmcnt(18)
	v_mul_f32_e32 v138, v144, v145
	s_waitcnt vmcnt(16)
	v_mul_f32_e32 v139, v146, v147
	ds_write2_b32 v35, v132, v133 offset1:66
	ds_write2_b32 v35, v134, v135 offset0:132 offset1:198
	ds_write2_b32 v52, v136, v137 offset0:8 offset1:74
	ds_write2_b32 v52, v138, v139 offset0:140 offset1:206
	v_add_u32_e32 v35, 0x840, v35
	v_add_u32_e32 v52, 0x400, v35
	s_waitcnt vmcnt(14)
; #define LAS __attribute__((address_space(3)))
; __device__ __forceinline__ unsigned cvtpk(float lo, float hi) { f32x2 v = {lo, hi}; bf16x2_t b = __builtin_convertvector(v, bf16x2_t); return __builtin_bit_cast(unsigned, b); }
; __device__ __forceinline__ void transpose_item(const float* W, int K, int N, bf16_t* WT, const float* gain, int mode, LAS float* scr, int item, int lane) {
;     ...
;     for (int i = 0; i < 32; ++i) { const int kk = 2 * i + (lane >> 5); float w = __builtin_nontemporal_load(W + (size_t)(k0 + kk) * N + n0 + (lane & 31)); if (gain) w *= gain[k0 + kk]; scr[kk * 33 + (lane & 31)] = w; }
;     int d0 = n0;
;     if (mode == 1) { const int j = n0 < DFF ? n0 : n0 - DFF; d0 = 256 * (j >> 7) + (j & 127) + (n0 < DFF ? 0 : 128); }
;     const int c = lane & 7;
; #pragma unroll
;     for (int j = 0; j < 4; ++j) { const int n = (lane >> 3) + 8 * j; const LAS float* s = scr + (8 * c) * 33 + n;
;         u32x4 o; o.x = cvtpk(s[0 * 33], s[1 * 33]); o.y = cvtpk(s[2 * 33], s[3 * 33]); o.z = cvtpk(s[4 * 33], s[5 * 33]); o.w = cvtpk(s[6 * 33], s[7 * 33]);
;         *(u32x4*)(WT + (size_t)(d0 + n) * K + k0 + 8 * c) = o; }
	v_mul_f32_e32 v148, v148, v149
	s_waitcnt vmcnt(12)
	v_mul_f32_e32 v149, v150, v151
	s_waitcnt vmcnt(10)
	v_mul_f32_e32 v150, v152, v153
	s_waitcnt vmcnt(8)
	v_mul_f32_e32 v151, v154, v155
	s_waitcnt vmcnt(6)
	v_mul_f32_e32 v152, v156, v157
	s_waitcnt vmcnt(4)
	v_mul_f32_e32 v153, v158, v159
	s_waitcnt vmcnt(2)
	v_mul_f32_e32 v154, v160, v161
	s_waitcnt vmcnt(0)
	v_mul_f32_e32 v155, v162, v163
	ds_write2_b32 v35, v148, v149 offset1:66
	ds_write2_b32 v35, v150, v151 offset0:132 offset1:198
	ds_write2_b32 v52, v152, v153 offset0:8 offset1:74
	ds_write2_b32 v52, v154, v155 offset0:140 offset1:206
	v_add_u32_e32 v35, 0x840, v35
	s_and_b32 s2, 0xffff, s16
	s_and_b32 s3, 0xffff, s11
	s_add_i32 s11, s2, 0xfffff500
	s_cmpk_lt_u32 s3, 0x58
	s_cselect_b32 s2, s2, s11
	s_cselect_b32 s3, 0, 0x80
	s_lshl_b32 s11, s2, 1
	s_and_b32 s2, s2, 0x60
	v_lshlrev_b32_e32 v0, 3, v34
	s_and_b32 s11, s11, 0xffffff00
	s_or_b32 s2, s2, s3
	v_ashrrev_i32_e32 v24, 3, v34
	v_and_b32_e32 v0, 56, v0
	s_or_b32 s11, s2, s11
	v_mul_u32_u24_e32 v2, 0x84, v0
	s_and_b32 s2, 0xffff, s10
	v_lshlrev_b32_e32 v3, 2, v24
	v_readlane_b32 s10, v254, 15
	s_lshl_b32 s2, s2, 1
	s_add_u32 s2, s6, s2
	v_add3_u32 v28, s10, v2, v3
	ds_read2_b32 v[6:7], v28 offset0:33 offset1:41
	ds_read2_b32 v[8:9], v28 offset1:8
	ds_read2_b32 v[10:11], v28 offset0:66 offset1:74
	ds_read2_b32 v[12:13], v28 offset0:99 offset1:107
	ds_read2_b32 v[14:15], v28 offset0:132 offset1:140
	ds_read2_b32 v[16:17], v28 offset0:165 offset1:173
	ds_read2_b32 v[18:19], v28 offset0:198 offset1:206
	ds_read2_b32 v[20:21], v28 offset0:231 offset1:239
	v_add_u32_e32 v24, s11, v24
	s_addc_u32 s3, s7, 0
	v_lshlrev_b32_e32 v0, 1, v0
	v_ashrrev_i32_e32 v25, 31, v24
	v_lshl_add_u64 v[22:23], s[2:3], 0, v[0:1]
	v_lshlrev_b64 v[26:27], 11, v[24:25]
	s_waitcnt lgkmcnt(6)
	v_cvt_pk_bf16_f32 v2, v8, v6
	s_waitcnt lgkmcnt(4)
	v_cvt_pk_bf16_f32 v3, v10, v12
	s_waitcnt lgkmcnt(2)
	v_cvt_pk_bf16_f32 v4, v14, v16
	s_waitcnt lgkmcnt(0)
	v_cvt_pk_bf16_f32 v5, v18, v20
	v_lshl_add_u64 v[26:27], v[22:23], 0, v[26:27]
	v_add_u32_e32 v6, 8, v24
	global_store_dwordx4 v[26:27], v[2:5], off
	s_nop 1
	v_cvt_pk_bf16_f32 v2, v9, v7
	v_ashrrev_i32_e32 v7, 31, v6
	v_cvt_pk_bf16_f32 v3, v11, v13
	v_cvt_pk_bf16_f32 v4, v15, v17
	v_cvt_pk_bf16_f32 v5, v19, v21
	v_lshlrev_b64 v[6:7], 11, v[6:7]
	ds_read2_b32 v[8:9], v28 offset0:49 offset1:57
	ds_read2_b32 v[10:11], v28 offset0:16 offset1:24
	ds_read2_b32 v[12:13], v28 offset0:82 offset1:90
	ds_read2_b32 v[14:15], v28 offset0:115 offset1:123
	ds_read2_b32 v[16:17], v28 offset0:148 offset1:156
	ds_read2_b32 v[18:19], v28 offset0:181 offset1:189
	ds_read2_b32 v[20:21], v28 offset0:214 offset1:222
	ds_read2_b32 v[26:27], v28 offset0:247 offset1:255
	v_lshl_add_u64 v[6:7], v[22:23], 0, v[6:7]
	global_store_dwordx4 v[6:7], v[2:5], off
	v_add_u32_e32 v6, 16, v24
	v_ashrrev_i32_e32 v7, 31, v6
	v_lshlrev_b64 v[6:7], 11, v[6:7]
	s_waitcnt lgkmcnt(6)
	v_cvt_pk_bf16_f32 v2, v10, v8
	s_waitcnt lgkmcnt(4)
	v_cvt_pk_bf16_f32 v3, v12, v14
	s_waitcnt lgkmcnt(2)
	v_cvt_pk_bf16_f32 v4, v16, v18
	s_waitcnt lgkmcnt(0)
	v_cvt_pk_bf16_f32 v5, v20, v26
	v_lshl_add_u64 v[6:7], v[22:23], 0, v[6:7]
	global_store_dwordx4 v[6:7], v[2:5], off
	v_add_u32_e32 v6, 24, v24
	v_ashrrev_i32_e32 v7, 31, v6
	v_lshlrev_b64 v[6:7], 11, v[6:7]
	v_cvt_pk_bf16_f32 v2, v11, v9
	v_cvt_pk_bf16_f32 v3, v13, v15
	v_cvt_pk_bf16_f32 v4, v17, v19
	v_cvt_pk_bf16_f32 v5, v21, v27
	v_lshl_add_u64 v[6:7], v[22:23], 0, v[6:7]
	global_store_dwordx4 v[6:7], v[2:5], off

; #define LAS __attribute__((address_space(3)))
; __device__ __forceinline__ unsigned cvtpk(float lo, float hi) { f32x2 v = {lo, hi}; bf16x2_t b = __builtin_convertvector(v, bf16x2_t); return __builtin_bit_cast(unsigned, b); }
; __device__ __forceinline__ void transpose_item(const float* W, int K, int N, bf16_t* WT, const float* gain, int mode, LAS float* scr, int item, int lane) {
;     ...
; #pragma unroll 8
;     for (int i = 0; i < 32; ++i) { const int kk = 2 * i + (lane >> 5); float w = __builtin_nontemporal_load(W + (size_t)(k0 + kk) * N + n0 + (lane & 31)); if (gain) w *= gain[k0 + kk]; scr[kk * 33 + (lane & 31)] = w; }
;     int d0 = n0;
;     if (mode == 1) { const int j = n0 < DFF ? n0 : n0 - DFF; d0 = 256 * (j >> 7) + (j & 127) + (n0 < DFF ? 0 : 128); }
;     const int c = lane & 7;
; #pragma unroll
;     for (int j = 0; j < 4; ++j) { const int n = (lane >> 3) + 8 * j; const LAS float* s = scr + (8 * c) * 33 + n;
;         u32x4 o; o.x = cvtpk(s[0 * 33], s[1 * 33]); o.y = cvtpk(s[2 * 33], s[3 * 33]); o.z = cvtpk(s[4 * 33], s[5 * 33]); o.w = cvtpk(s[6 * 33], s[7 * 33]);
;         *(u32x4*)(WT + (size_t)(d0 + n) * K + k0 + 8 * c) = o; }
.LBB0_347:
	v_lshl_add_u64 v[20:21], v[16:17], 0, s[2:3]
	v_lshl_add_u64 v[22:23], v[14:15], 0, s[2:3]
	v_lshl_add_u64 v[24:25], v[12:13], 0, s[2:3]
	v_lshl_add_u64 v[26:27], v[10:11], 0, s[2:3]
	v_lshl_add_u64 v[28:29], v[8:9], 0, s[2:3]
	v_lshl_add_u64 v[30:31], v[6:7], 0, s[2:3]
	v_lshl_add_u64 v[32:33], v[4:5], 0, s[2:3]
	s_waitcnt vmcnt(0)
	v_lshl_add_u64 v[34:35], v[2:3], 0, s[2:3]
	global_load_dword v100, v[20:21], off nt
	s_nop 0
	global_load_dword v101, v[22:23], off nt
	global_load_dword v102, v[24:25], off nt
	s_nop 0
	global_load_dword v103, v[26:27], off nt
	global_load_dword v104, v[28:29], off nt
	global_load_dword v105, v[30:31], off nt
	global_load_dword v106, v[32:33], off nt
	s_nop 0
	global_load_dword v107, v[34:35], off nt
	s_add_u32 s2, s2, 0x10000
	s_addc_u32 s3, s3, 0
	v_lshl_add_u64 v[20:21], v[16:17], 0, s[2:3]
	v_lshl_add_u64 v[22:23], v[14:15], 0, s[2:3]
	v_lshl_add_u64 v[24:25], v[12:13], 0, s[2:3]
	v_lshl_add_u64 v[26:27], v[10:11], 0, s[2:3]
	v_lshl_add_u64 v[28:29], v[8:9], 0, s[2:3]
	v_lshl_add_u64 v[30:31], v[6:7], 0, s[2:3]
	v_lshl_add_u64 v[32:33], v[4:5], 0, s[2:3]
	v_lshl_add_u64 v[34:35], v[2:3], 0, s[2:3]
	global_load_dword v116, v[20:21], off nt
	s_nop 0
	global_load_dword v117, v[22:23], off nt
	global_load_dword v118, v[24:25], off nt
	s_nop 0
	global_load_dword v119, v[26:27], off nt
	global_load_dword v120, v[28:29], off nt
	global_load_dword v121, v[30:31], off nt
	global_load_dword v122, v[32:33], off nt
	s_nop 0
	global_load_dword v123, v[34:35], off nt
	s_add_u32 s2, s2, 0x10000
	s_addc_u32 s3, s3, 0
	v_lshl_add_u64 v[20:21], v[16:17], 0, s[2:3]
	v_lshl_add_u64 v[22:23], v[14:15], 0, s[2:3]
	v_lshl_add_u64 v[24:25], v[12:13], 0, s[2:3]
	v_lshl_add_u64 v[26:27], v[10:11], 0, s[2:3]
	v_lshl_add_u64 v[28:29], v[8:9], 0, s[2:3]
	v_lshl_add_u64 v[30:31], v[6:7], 0, s[2:3]
	v_lshl_add_u64 v[32:33], v[4:5], 0, s[2:3]
	v_lshl_add_u64 v[34:35], v[2:3], 0, s[2:3]
	global_load_dword v132, v[20:21], off nt
	s_nop 0
	global_load_dword v133, v[22:23], off nt
	global_load_dword v134, v[24:25], off nt
	s_nop 0
	global_load_dword v135, v[26:27], off nt
	global_load_dword v136, v[28:29], off nt
	global_load_dword v137, v[30:31], off nt
	global_load_dword v138, v[32:33], off nt
	s_nop 0
	global_load_dword v139, v[34:35], off nt
	s_add_u32 s2, s2, 0x10000
	s_addc_u32 s3, s3, 0
	v_lshl_add_u64 v[20:21], v[16:17], 0, s[2:3]
	v_lshl_add_u64 v[22:23], v[14:15], 0, s[2:3]
	v_lshl_add_u64 v[24:25], v[12:13], 0, s[2:3]
	v_lshl_add_u64 v[26:27], v[10:11], 0, s[2:3]
	v_lshl_add_u64 v[28:29], v[8:9], 0, s[2:3]
	v_lshl_add_u64 v[30:31], v[6:7], 0, s[2:3]
	v_lshl_add_u64 v[32:33], v[4:5], 0, s[2:3]
	v_lshl_add_u64 v[34:35], v[2:3], 0, s[2:3]
	global_load_dword v148, v[20:21], off nt
	s_nop 0
	global_load_dword v149, v[22:23], off nt
	global_load_dword v150, v[24:25], off nt
	s_nop 0
	global_load_dword v151, v[26:27], off nt
	global_load_dword v152, v[28:29], off nt
	global_load_dword v153, v[30:31], off nt
	global_load_dword v154, v[32:33], off nt
	s_nop 0
	global_load_dword v155, v[34:35], off nt
	s_add_u32 s2, s2, 0x10000
	s_addc_u32 s3, s3, 0
	v_add_u32_e32 v27, 0x400, v19
	s_waitcnt vmcnt(30)
	ds_write2_b32 v19, v100, v101 offset1:66
	s_waitcnt vmcnt(28)
	ds_write2_b32 v19, v102, v103 offset0:132 offset1:198
	s_waitcnt vmcnt(26)
	ds_write2_b32 v27, v104, v105 offset0:8 offset1:74
	s_waitcnt vmcnt(24)
	ds_write2_b32 v27, v106, v107 offset0:140 offset1:206
	v_add_u32_e32 v19, 0x840, v19
	v_add_u32_e32 v27, 0x400, v19
	s_waitcnt vmcnt(22)
	ds_write2_b32 v19, v116, v117 offset1:66
	s_waitcnt vmcnt(20)
; #define LAS __attribute__((address_space(3)))
; __device__ __forceinline__ unsigned cvtpk(float lo, float hi) { f32x2 v = {lo, hi}; bf16x2_t b = __builtin_convertvector(v, bf16x2_t); return __builtin_bit_cast(unsigned, b); }
; __device__ __forceinline__ void transpose_item(const float* W, int K, int N, bf16_t* WT, const float* gain, int mode, LAS float* scr, int item, int lane) {
;     ...
;     for (int i = 0; i < 32; ++i) { const int kk = 2 * i + (lane >> 5); float w = __builtin_nontemporal_load(W + (size_t)(k0 + kk) * N + n0 + (lane & 31)); if (gain) w *= gain[k0 + kk]; scr[kk * 33 + (lane & 31)] = w; }
;     int d0 = n0;
;     if (mode == 1) { const int j = n0 < DFF ? n0 : n0 - DFF; d0 = 256 * (j >> 7) + (j & 127) + (n0 < DFF ? 0 : 128); }
;     const int c = lane & 7;
; #pragma unroll
;     for (int j = 0; j < 4; ++j) { const int n = (lane >> 3) + 8 * j; const LAS float* s = scr + (8 * c) * 33 + n;
;         u32x4 o; o.x = cvtpk(s[0 * 33], s[1 * 33]); o.y = cvtpk(s[2 * 33], s[3 * 33]); o.z = cvtpk(s[4 * 33], s[5 * 33]); o.w = cvtpk(s[6 * 33], s[7 * 33]);
;         *(u32x4*)(WT + (size_t)(d0 + n) * K + k0 + 8 * c) = o; }
	ds_write2_b32 v19, v118, v119 offset0:132 offset1:198
	s_waitcnt vmcnt(18)
	ds_write2_b32 v27, v120, v121 offset0:8 offset1:74
	s_waitcnt vmcnt(16)
	ds_write2_b32 v27, v122, v123 offset0:140 offset1:206
	v_add_u32_e32 v19, 0x840, v19
	v_add_u32_e32 v27, 0x400, v19
	s_waitcnt vmcnt(14)
	ds_write2_b32 v19, v132, v133 offset1:66
	s_waitcnt vmcnt(12)
	ds_write2_b32 v19, v134, v135 offset0:132 offset1:198
	s_waitcnt vmcnt(10)
	ds_write2_b32 v27, v136, v137 offset0:8 offset1:74
	s_waitcnt vmcnt(8)
	ds_write2_b32 v27, v138, v139 offset0:140 offset1:206
	v_add_u32_e32 v19, 0x840, v19
	v_add_u32_e32 v27, 0x400, v19
	s_waitcnt vmcnt(6)
	ds_write2_b32 v19, v148, v149 offset1:66
	s_waitcnt vmcnt(4)
	ds_write2_b32 v19, v150, v151 offset0:132 offset1:198
	s_waitcnt vmcnt(2)
	ds_write2_b32 v27, v152, v153 offset0:8 offset1:74
	s_waitcnt vmcnt(0)
	ds_write2_b32 v27, v154, v155 offset0:140 offset1:206
	v_add_u32_e32 v19, 0x840, v19
	v_lshlrev_b32_e32 v0, 3, v18
	v_ashrrev_i32_e32 v24, 3, v18
	v_and_b32_e32 v0, 56, v0
	s_lshl_b32 s2, s36, 1
	v_mul_u32_u24_e32 v2, 0x84, v0
	v_lshlrev_b32_e32 v3, 2, v24
	v_readlane_b32 s11, v254, 15
	s_add_i32 s2, s2, 0x1e700
	s_and_b32 s2, s2, 0x1ffc0
	v_add3_u32 v28, s11, v2, v3
	s_lshl_b32 s3, s36, 5
	ds_read2_b32 v[6:7], v28 offset0:33 offset1:41
	ds_read2_b32 v[8:9], v28 offset1:8
	ds_read2_b32 v[10:11], v28 offset0:66 offset1:74
	ds_read2_b32 v[12:13], v28 offset0:99 offset1:107
	ds_read2_b32 v[14:15], v28 offset0:132 offset1:140
	ds_read2_b32 v[16:17], v28 offset0:165 offset1:173
	ds_read2_b32 v[18:19], v28 offset0:198 offset1:206
	ds_read2_b32 v[20:21], v28 offset0:231 offset1:239
	s_and_b32 s10, s3, 0x3e0
	s_lshl_b32 s2, s2, 1
	s_add_u32 s2, s12, s2
	v_add_u32_e32 v24, s10, v24
	s_addc_u32 s3, s13, 0
	v_lshlrev_b32_e32 v0, 1, v0
	v_ashrrev_i32_e32 v25, 31, v24
	v_lshl_add_u64 v[22:23], s[2:3], 0, v[0:1]
	v_lshlrev_b64 v[26:27], 11, v[24:25]
	s_waitcnt lgkmcnt(6)
	v_cvt_pk_bf16_f32 v2, v8, v6
	s_waitcnt lgkmcnt(4)
	v_cvt_pk_bf16_f32 v3, v10, v12
	s_waitcnt lgkmcnt(2)
	v_cvt_pk_bf16_f32 v4, v14, v16
	s_waitcnt lgkmcnt(0)
	v_cvt_pk_bf16_f32 v5, v18, v20
	v_lshl_add_u64 v[26:27], v[22:23], 0, v[26:27]
	v_add_u32_e32 v6, 8, v24
	global_store_dwordx4 v[26:27], v[2:5], off
	s_nop 1
	v_cvt_pk_bf16_f32 v2, v9, v7
	v_ashrrev_i32_e32 v7, 31, v6
	v_cvt_pk_bf16_f32 v3, v11, v13
	v_cvt_pk_bf16_f32 v4, v15, v17
	v_cvt_pk_bf16_f32 v5, v19, v21
	v_lshlrev_b64 v[6:7], 11, v[6:7]
	ds_read2_b32 v[8:9], v28 offset0:49 offset1:57
	ds_read2_b32 v[10:11], v28 offset0:16 offset1:24
	ds_read2_b32 v[12:13], v28 offset0:82 offset1:90
	ds_read2_b32 v[14:15], v28 offset0:115 offset1:123
	ds_read2_b32 v[16:17], v28 offset0:148 offset1:156
	ds_read2_b32 v[18:19], v28 offset0:181 offset1:189
	ds_read2_b32 v[20:21], v28 offset0:214 offset1:222
	ds_read2_b32 v[26:27], v28 offset0:247 offset1:255
	v_lshl_add_u64 v[6:7], v[22:23], 0, v[6:7]
	global_store_dwordx4 v[6:7], v[2:5], off
	v_add_u32_e32 v6, 16, v24
	v_ashrrev_i32_e32 v7, 31, v6
	v_lshlrev_b64 v[6:7], 11, v[6:7]
	s_waitcnt lgkmcnt(6)
	v_cvt_pk_bf16_f32 v2, v10, v8
	s_waitcnt lgkmcnt(4)
	v_cvt_pk_bf16_f32 v3, v12, v14
	s_waitcnt lgkmcnt(2)
	v_cvt_pk_bf16_f32 v4, v16, v18
	s_waitcnt lgkmcnt(0)
	v_cvt_pk_bf16_f32 v5, v20, v26
	v_lshl_add_u64 v[6:7], v[22:23], 0, v[6:7]
	global_store_dwordx4 v[6:7], v[2:5], off
	v_add_u32_e32 v6, 24, v24
	v_ashrrev_i32_e32 v7, 31, v6
	v_lshlrev_b64 v[6:7], 11, v[6:7]
	v_cvt_pk_bf16_f32 v2, v11, v9
	v_cvt_pk_bf16_f32 v3, v13, v15
	v_cvt_pk_bf16_f32 v4, v17, v19
	v_cvt_pk_bf16_f32 v5, v21, v27
	v_lshl_add_u64 v[6:7], v[22:23], 0, v[6:7]
	global_store_dwordx4 v[6:7], v[2:5], off

; __device__ __forceinline__ void transpose_item(const float* W, int K, int N, bf16_t* WT, const float* gain, int mode, LAS float* scr, int item, int lane) {
;     ...
; #pragma unroll 8
;     for (int i = 0; i < 32; ++i) { const int kk = 2 * i + (lane >> 5); float w = __builtin_nontemporal_load(W + (size_t)(k0 + kk) * N + n0 + (lane & 31)); if (gain) w *= gain[k0 + kk]; scr[kk * 33 + (lane & 31)] = w; }
.LBB0_352:
	v_lshl_add_u64 v[36:37], v[30:31], 0, v[0:1]
	v_lshl_add_u64 v[38:39], v[32:33], 0, s[10:11]
	v_lshl_add_u64 v[40:41], v[28:29], 0, v[0:1]
	v_lshl_add_u64 v[42:43], v[26:27], 0, s[10:11]
	v_lshl_add_u64 v[44:45], v[24:25], 0, v[0:1]
	v_lshl_add_u64 v[46:47], v[22:23], 0, s[10:11]
	v_lshl_add_u64 v[48:49], v[20:21], 0, v[0:1]
	v_lshl_add_u64 v[50:51], v[18:19], 0, s[10:11]
	v_lshl_add_u64 v[52:53], v[16:17], 0, v[0:1]
	v_lshl_add_u64 v[54:55], v[14:15], 0, s[10:11]
	v_lshl_add_u64 v[56:57], v[12:13], 0, v[0:1]
	v_lshl_add_u64 v[58:59], v[10:11], 0, s[10:11]
	v_lshl_add_u64 v[60:61], v[8:9], 0, v[0:1]
	v_lshl_add_u64 v[62:63], v[6:7], 0, s[10:11]
	v_lshl_add_u64 v[64:65], v[4:5], 0, v[0:1]
	v_lshl_add_u64 v[66:67], v[2:3], 0, s[10:11]
	global_load_dword v100, v[36:37], off nt
	s_nop 0
	global_load_dword v101, v[38:39], off
	s_nop 0
	global_load_dword v102, v[40:41], off nt
	global_load_dword v103, v[42:43], off
	s_nop 0
	global_load_dword v104, v[44:45], off nt
	global_load_dword v105, v[46:47], off
	global_load_dword v106, v[48:49], off nt
	global_load_dword v107, v[50:51], off
	s_nop 0
	global_load_dword v108, v[52:53], off nt
	global_load_dword v109, v[54:55], off
	global_load_dword v110, v[56:57], off nt
	global_load_dword v111, v[58:59], off
	global_load_dword v112, v[60:61], off nt
	global_load_dword v113, v[62:63], off
	global_load_dword v114, v[64:65], off nt
	global_load_dword v115, v[66:67], off
	s_add_u32 s10, s10, 64
	s_addc_u32 s11, s11, 0
	v_lshl_add_u64 v[4:5], v[4:5], 0, s[16:17]
	v_lshl_add_u64 v[8:9], v[8:9], 0, s[16:17]
	v_lshl_add_u64 v[12:13], v[12:13], 0, s[16:17]
	v_lshl_add_u64 v[16:17], v[16:17], 0, s[16:17]
	v_lshl_add_u64 v[20:21], v[20:21], 0, s[16:17]
	v_lshl_add_u64 v[24:25], v[24:25], 0, s[16:17]
	v_lshl_add_u64 v[28:29], v[28:29], 0, s[16:17]
	v_lshl_add_u64 v[30:31], v[30:31], 0, s[16:17]
	v_lshl_add_u64 v[36:37], v[30:31], 0, v[0:1]
	v_lshl_add_u64 v[38:39], v[32:33], 0, s[10:11]
	v_lshl_add_u64 v[40:41], v[28:29], 0, v[0:1]
	v_lshl_add_u64 v[42:43], v[26:27], 0, s[10:11]
	v_lshl_add_u64 v[44:45], v[24:25], 0, v[0:1]
	v_lshl_add_u64 v[46:47], v[22:23], 0, s[10:11]
	v_lshl_add_u64 v[48:49], v[20:21], 0, v[0:1]
	v_lshl_add_u64 v[50:51], v[18:19], 0, s[10:11]
	v_lshl_add_u64 v[52:53], v[16:17], 0, v[0:1]
	v_lshl_add_u64 v[54:55], v[14:15], 0, s[10:11]
	v_lshl_add_u64 v[56:57], v[12:13], 0, v[0:1]
	v_lshl_add_u64 v[58:59], v[10:11], 0, s[10:11]
	v_lshl_add_u64 v[60:61], v[8:9], 0, v[0:1]
	v_lshl_add_u64 v[62:63], v[6:7], 0, s[10:11]
	v_lshl_add_u64 v[64:65], v[4:5], 0, v[0:1]
	v_lshl_add_u64 v[66:67], v[2:3], 0, s[10:11]
	global_load_dword v116, v[36:37], off nt
	s_nop 0
	global_load_dword v117, v[38:39], off
	s_nop 0
	global_load_dword v118, v[40:41], off nt
	global_load_dword v119, v[42:43], off
	s_nop 0
	global_load_dword v120, v[44:45], off nt
	global_load_dword v121, v[46:47], off
	global_load_dword v122, v[48:49], off nt
	global_load_dword v123, v[50:51], off
	s_nop 0
	global_load_dword v124, v[52:53], off nt
	global_load_dword v125, v[54:55], off
	global_load_dword v126, v[56:57], off nt
	global_load_dword v127, v[58:59], off
	global_load_dword v128, v[60:61], off nt
	global_load_dword v129, v[62:63], off
	global_load_dword v130, v[64:65], off nt
	global_load_dword v131, v[66:67], off
	s_add_u32 s10, s10, 64
	s_addc_u32 s11, s11, 0
	v_lshl_add_u64 v[4:5], v[4:5], 0, s[16:17]
	v_lshl_add_u64 v[8:9], v[8:9], 0, s[16:17]
	v_lshl_add_u64 v[12:13], v[12:13], 0, s[16:17]
	v_lshl_add_u64 v[16:17], v[16:17], 0, s[16:17]
	v_lshl_add_u64 v[20:21], v[20:21], 0, s[16:17]
	v_lshl_add_u64 v[24:25], v[24:25], 0, s[16:17]
	v_lshl_add_u64 v[28:29], v[28:29], 0, s[16:17]
	v_lshl_add_u64 v[30:31], v[30:31], 0, s[16:17]
	v_lshl_add_u64 v[36:37], v[30:31], 0, v[0:1]
	v_lshl_add_u64 v[38:39], v[32:33], 0, s[10:11]
	v_lshl_add_u64 v[40:41], v[28:29], 0, v[0:1]
	v_lshl_add_u64 v[42:43], v[26:27], 0, s[10:11]
	v_lshl_add_u64 v[44:45], v[24:25], 0, v[0:1]
	v_lshl_add_u64 v[46:47], v[22:23], 0, s[10:11]
	v_lshl_add_u64 v[48:49], v[20:21], 0, v[0:1]
	v_lshl_add_u64 v[50:51], v[18:19], 0, s[10:11]
	v_lshl_add_u64 v[52:53], v[16:17], 0, v[0:1]
	v_lshl_add_u64 v[54:55], v[14:15], 0, s[10:11]
	v_lshl_add_u64 v[56:57], v[12:13], 0, v[0:1]
	v_lshl_add_u64 v[58:59], v[10:11], 0, s[10:11]
	v_lshl_add_u64 v[60:61], v[8:9], 0, v[0:1]
	v_lshl_add_u64 v[62:63], v[6:7], 0, s[10:11]
	v_lshl_add_u64 v[64:65], v[4:5], 0, v[0:1]
	v_lshl_add_u64 v[66:67], v[2:3], 0, s[10:11]
	global_load_dword v132, v[36:37], off nt
	s_nop 0
	global_load_dword v133, v[38:39], off
	s_nop 0
	global_load_dword v134, v[40:41], off nt
	global_load_dword v135, v[42:43], off
	s_nop 0
	global_load_dword v136, v[44:45], off nt
	global_load_dword v137, v[46:47], off
	global_load_dword v138, v[48:49], off nt
	global_load_dword v139, v[50:51], off
	s_nop 0
	global_load_dword v140, v[52:53], off nt
	global_load_dword v141, v[54:55], off
	global_load_dword v142, v[56:57], off nt
	global_load_dword v143, v[58:59], off
	global_load_dword v144, v[60:61], off nt
	global_load_dword v145, v[62:63], off
	global_load_dword v146, v[64:65], off nt
	global_load_dword v147, v[66:67], off
	s_add_u32 s10, s10, 64
	s_addc_u32 s11, s11, 0
	v_lshl_add_u64 v[4:5], v[4:5], 0, s[16:17]
	v_lshl_add_u64 v[8:9], v[8:9], 0, s[16:17]
	v_lshl_add_u64 v[12:13], v[12:13], 0, s[16:17]
	v_lshl_add_u64 v[16:17], v[16:17], 0, s[16:17]
	v_lshl_add_u64 v[20:21], v[20:21], 0, s[16:17]
	v_lshl_add_u64 v[24:25], v[24:25], 0, s[16:17]
	v_lshl_add_u64 v[28:29], v[28:29], 0, s[16:17]
	v_lshl_add_u64 v[30:31], v[30:31], 0, s[16:17]
	v_lshl_add_u64 v[36:37], v[30:31], 0, v[0:1]
	v_lshl_add_u64 v[38:39], v[32:33], 0, s[10:11]
; __device__ __forceinline__ void transpose_item(const float* W, int K, int N, bf16_t* WT, const float* gain, int mode, LAS float* scr, int item, int lane) {
;     ...
; #pragma unroll 8
;     for (int i = 0; i < 32; ++i) { const int kk = 2 * i + (lane >> 5); float w = __builtin_nontemporal_load(W + (size_t)(k0 + kk) * N + n0 + (lane & 31)); if (gain) w *= gain[k0 + kk]; scr[kk * 33 + (lane & 31)] = w; }
	v_lshl_add_u64 v[40:41], v[28:29], 0, v[0:1]
	v_lshl_add_u64 v[42:43], v[26:27], 0, s[10:11]
	v_lshl_add_u64 v[44:45], v[24:25], 0, v[0:1]
	v_lshl_add_u64 v[46:47], v[22:23], 0, s[10:11]
	v_lshl_add_u64 v[48:49], v[20:21], 0, v[0:1]
	v_lshl_add_u64 v[50:51], v[18:19], 0, s[10:11]
	v_lshl_add_u64 v[52:53], v[16:17], 0, v[0:1]
	v_lshl_add_u64 v[54:55], v[14:15], 0, s[10:11]
	v_lshl_add_u64 v[56:57], v[12:13], 0, v[0:1]
	v_lshl_add_u64 v[58:59], v[10:11], 0, s[10:11]
	v_lshl_add_u64 v[60:61], v[8:9], 0, v[0:1]
	v_lshl_add_u64 v[62:63], v[6:7], 0, s[10:11]
	v_lshl_add_u64 v[64:65], v[4:5], 0, v[0:1]
	v_lshl_add_u64 v[66:67], v[2:3], 0, s[10:11]
	global_load_dword v148, v[36:37], off nt
	s_nop 0
	global_load_dword v149, v[38:39], off
	s_nop 0
	global_load_dword v150, v[40:41], off nt
	global_load_dword v151, v[42:43], off
	s_nop 0
	global_load_dword v152, v[44:45], off nt
	global_load_dword v153, v[46:47], off
	global_load_dword v154, v[48:49], off nt
	global_load_dword v155, v[50:51], off
	s_nop 0
	global_load_dword v156, v[52:53], off nt
	global_load_dword v157, v[54:55], off
	global_load_dword v158, v[56:57], off nt
	global_load_dword v159, v[58:59], off
	global_load_dword v160, v[60:61], off nt
	global_load_dword v161, v[62:63], off
	global_load_dword v162, v[64:65], off nt
	global_load_dword v163, v[66:67], off
	s_add_u32 s10, s10, 64
	s_addc_u32 s11, s11, 0
	v_lshl_add_u64 v[4:5], v[4:5], 0, s[16:17]
	v_lshl_add_u64 v[8:9], v[8:9], 0, s[16:17]
	v_lshl_add_u64 v[12:13], v[12:13], 0, s[16:17]
	v_lshl_add_u64 v[16:17], v[16:17], 0, s[16:17]
	v_lshl_add_u64 v[20:21], v[20:21], 0, s[16:17]
	v_lshl_add_u64 v[24:25], v[24:25], 0, s[16:17]
	v_lshl_add_u64 v[28:29], v[28:29], 0, s[16:17]
	v_lshl_add_u64 v[30:31], v[30:31], 0, s[16:17]
	v_add_u32_e32 v52, 0x400, v35
	s_waitcnt vmcnt(62)
	v_mul_f32_e32 v100, v100, v101
	s_waitcnt vmcnt(60)
	v_mul_f32_e32 v101, v102, v103
	s_waitcnt vmcnt(58)
	v_mul_f32_e32 v102, v104, v105
	s_waitcnt vmcnt(56)
	v_mul_f32_e32 v103, v106, v107
	s_waitcnt vmcnt(54)
	v_mul_f32_e32 v104, v108, v109
	s_waitcnt vmcnt(52)
	v_mul_f32_e32 v105, v110, v111
	s_waitcnt vmcnt(50)
	v_mul_f32_e32 v106, v112, v113
	s_waitcnt vmcnt(48)
	v_mul_f32_e32 v107, v114, v115
	ds_write2_b32 v35, v100, v101 offset1:66
	ds_write2_b32 v35, v102, v103 offset0:132 offset1:198
	ds_write2_b32 v52, v104, v105 offset0:8 offset1:74
	ds_write2_b32 v52, v106, v107 offset0:140 offset1:206
	v_add_u32_e32 v35, 0x840, v35
	v_add_u32_e32 v52, 0x400, v35
	s_waitcnt vmcnt(46)
	v_mul_f32_e32 v116, v116, v117
	s_waitcnt vmcnt(44)
	v_mul_f32_e32 v117, v118, v119
	s_waitcnt vmcnt(42)
	v_mul_f32_e32 v118, v120, v121
	s_waitcnt vmcnt(40)
	v_mul_f32_e32 v119, v122, v123
	s_waitcnt vmcnt(38)
	v_mul_f32_e32 v120, v124, v125
	s_waitcnt vmcnt(36)
	v_mul_f32_e32 v121, v126, v127
	s_waitcnt vmcnt(34)
	v_mul_f32_e32 v122, v128, v129
	s_waitcnt vmcnt(32)
	v_mul_f32_e32 v123, v130, v131
	ds_write2_b32 v35, v116, v117 offset1:66
	ds_write2_b32 v35, v118, v119 offset0:132 offset1:198
	ds_write2_b32 v52, v120, v121 offset0:8 offset1:74
	ds_write2_b32 v52, v122, v123 offset0:140 offset1:206
	v_add_u32_e32 v35, 0x840, v35
	v_add_u32_e32 v52, 0x400, v35
	s_waitcnt vmcnt(30)
	v_mul_f32_e32 v132, v132, v133
	s_waitcnt vmcnt(28)
	v_mul_f32_e32 v133, v134, v135
	s_waitcnt vmcnt(26)
	v_mul_f32_e32 v134, v136, v137
	s_waitcnt vmcnt(24)
	v_mul_f32_e32 v135, v138, v139
	s_waitcnt vmcnt(22)
	v_mul_f32_e32 v136, v140, v141
	s_waitcnt vmcnt(20)
	v_mul_f32_e32 v137, v142, v143
	s_waitcnt vmcnt(18)
	v_mul_f32_e32 v138, v144, v145
	s_waitcnt vmcnt(16)
; #define LAS __attribute__((address_space(3)))
; __device__ __forceinline__ unsigned cvtpk(float lo, float hi) { f32x2 v = {lo, hi}; bf16x2_t b = __builtin_convertvector(v, bf16x2_t); return __builtin_bit_cast(unsigned, b); }
; __device__ __forceinline__ void transpose_item(const float* W, int K, int N, bf16_t* WT, const float* gain, int mode, LAS float* scr, int item, int lane) {
;     ...
;     for (int i = 0; i < 32; ++i) { const int kk = 2 * i + (lane >> 5); float w = __builtin_nontemporal_load(W + (size_t)(k0 + kk) * N + n0 + (lane & 31)); if (gain) w *= gain[k0 + kk]; scr[kk * 33 + (lane & 31)] = w; }
;     int d0 = n0;
;     if (mode == 1) { const int j = n0 < DFF ? n0 : n0 - DFF; d0 = 256 * (j >> 7) + (j & 127) + (n0 < DFF ? 0 : 128); }
;     const int c = lane & 7;
; #pragma unroll
;     for (int j = 0; j < 4; ++j) { const int n = (lane >> 3) + 8 * j; const LAS float* s = scr + (8 * c) * 33 + n;
;         u32x4 o; o.x = cvtpk(s[0 * 33], s[1 * 33]); o.y = cvtpk(s[2 * 33], s[3 * 33]); o.z = cvtpk(s[4 * 33], s[5 * 33]); o.w = cvtpk(s[6 * 33], s[7 * 33]);
;         *(u32x4*)(WT + (size_t)(d0 + n) * K + k0 + 8 * c) = o; }
	v_mul_f32_e32 v139, v146, v147
	ds_write2_b32 v35, v132, v133 offset1:66
	ds_write2_b32 v35, v134, v135 offset0:132 offset1:198
	ds_write2_b32 v52, v136, v137 offset0:8 offset1:74
	ds_write2_b32 v52, v138, v139 offset0:140 offset1:206
	v_add_u32_e32 v35, 0x840, v35
	v_add_u32_e32 v52, 0x400, v35
	s_waitcnt vmcnt(14)
	v_mul_f32_e32 v148, v148, v149
	s_waitcnt vmcnt(12)
	v_mul_f32_e32 v149, v150, v151
	s_waitcnt vmcnt(10)
	v_mul_f32_e32 v150, v152, v153
	s_waitcnt vmcnt(8)
	v_mul_f32_e32 v151, v154, v155
	s_waitcnt vmcnt(6)
	v_mul_f32_e32 v152, v156, v157
	s_waitcnt vmcnt(4)
	v_mul_f32_e32 v153, v158, v159
	s_waitcnt vmcnt(2)
	v_mul_f32_e32 v154, v160, v161
	s_waitcnt vmcnt(0)
	v_mul_f32_e32 v155, v162, v163
	ds_write2_b32 v35, v148, v149 offset1:66
	ds_write2_b32 v35, v150, v151 offset0:132 offset1:198
	ds_write2_b32 v52, v152, v153 offset0:8 offset1:74
	ds_write2_b32 v52, v154, v155 offset0:140 offset1:206
	v_add_u32_e32 v35, 0x840, v35
	v_lshlrev_b32_e32 v0, 3, v34
	v_ashrrev_i32_e32 v24, 3, v34
	v_and_b32_e32 v0, 56, v0
	v_mul_u32_u24_e32 v2, 0x84, v0
	v_lshlrev_b32_e32 v3, 2, v24
	v_readlane_b32 s11, v254, 15
	s_and_b32 s2, 0xffff, s2
	s_and_b32 s10, 0xffff, s3
	v_add3_u32 v28, s11, v2, v3
	ds_read2_b32 v[6:7], v28 offset0:33 offset1:41
	ds_read2_b32 v[8:9], v28 offset1:8
	ds_read2_b32 v[10:11], v28 offset0:66 offset1:74
	ds_read2_b32 v[12:13], v28 offset0:99 offset1:107
	ds_read2_b32 v[14:15], v28 offset0:132 offset1:140
	ds_read2_b32 v[16:17], v28 offset0:165 offset1:173
	ds_read2_b32 v[18:19], v28 offset0:198 offset1:206
	ds_read2_b32 v[20:21], v28 offset0:231 offset1:239
	s_lshl_b32 s2, s2, 1
	s_add_u32 s2, s20, s2
	v_add_u32_e32 v24, s10, v24
	s_addc_u32 s3, s21, 0
	v_lshlrev_b32_e32 v0, 1, v0
	v_ashrrev_i32_e32 v25, 31, v24
	v_lshl_add_u64 v[22:23], s[2:3], 0, v[0:1]
	v_lshlrev_b64 v[26:27], 11, v[24:25]
	s_waitcnt lgkmcnt(6)
	v_cvt_pk_bf16_f32 v2, v8, v6
	s_waitcnt lgkmcnt(4)
	v_cvt_pk_bf16_f32 v3, v10, v12
	s_waitcnt lgkmcnt(2)
	v_cvt_pk_bf16_f32 v4, v14, v16
	s_waitcnt lgkmcnt(0)
	v_cvt_pk_bf16_f32 v5, v18, v20
	v_lshl_add_u64 v[26:27], v[22:23], 0, v[26:27]
	v_add_u32_e32 v6, 8, v24
	global_store_dwordx4 v[26:27], v[2:5], off
	s_nop 1
	v_cvt_pk_bf16_f32 v2, v9, v7
	v_ashrrev_i32_e32 v7, 31, v6
	v_cvt_pk_bf16_f32 v3, v11, v13
	v_cvt_pk_bf16_f32 v4, v15, v17
	v_cvt_pk_bf16_f32 v5, v19, v21
	v_lshlrev_b64 v[6:7], 11, v[6:7]
	ds_read2_b32 v[8:9], v28 offset0:49 offset1:57
	ds_read2_b32 v[10:11], v28 offset0:16 offset1:24
	ds_read2_b32 v[12:13], v28 offset0:82 offset1:90
	ds_read2_b32 v[14:15], v28 offset0:115 offset1:123
	ds_read2_b32 v[16:17], v28 offset0:148 offset1:156
	ds_read2_b32 v[18:19], v28 offset0:181 offset1:189
	ds_read2_b32 v[20:21], v28 offset0:214 offset1:222
	ds_read2_b32 v[26:27], v28 offset0:247 offset1:255
	v_lshl_add_u64 v[6:7], v[22:23], 0, v[6:7]
	global_store_dwordx4 v[6:7], v[2:5], off
	v_add_u32_e32 v6, 16, v24
	v_ashrrev_i32_e32 v7, 31, v6
	v_lshlrev_b64 v[6:7], 11, v[6:7]
	s_waitcnt lgkmcnt(6)
	v_cvt_pk_bf16_f32 v2, v10, v8
	s_waitcnt lgkmcnt(4)
	v_cvt_pk_bf16_f32 v3, v12, v14
	s_waitcnt lgkmcnt(2)
	v_cvt_pk_bf16_f32 v4, v16, v18
	s_waitcnt lgkmcnt(0)
	v_cvt_pk_bf16_f32 v5, v20, v26
	v_lshl_add_u64 v[6:7], v[22:23], 0, v[6:7]
	global_store_dwordx4 v[6:7], v[2:5], off
	v_add_u32_e32 v6, 24, v24
	v_ashrrev_i32_e32 v7, 31, v6
	v_lshlrev_b64 v[6:7], 11, v[6:7]
	v_cvt_pk_bf16_f32 v2, v11, v9
	v_cvt_pk_bf16_f32 v3, v13, v15
	v_cvt_pk_bf16_f32 v4, v17, v19
	v_cvt_pk_bf16_f32 v5, v21, v27
	v_lshl_add_u64 v[6:7], v[22:23], 0, v[6:7]
	global_store_dwordx4 v[6:7], v[2:5], off

; #define LAS __attribute__((address_space(3)))
; __device__ __forceinline__ unsigned cvtpk(float lo, float hi) { f32x2 v = {lo, hi}; bf16x2_t b = __builtin_convertvector(v, bf16x2_t); return __builtin_bit_cast(unsigned, b); }
; __device__ __forceinline__ void transpose_item(const float* W, int K, int N, bf16_t* WT, const float* gain, int mode, LAS float* scr, int item, int lane) {
;     ...
; #pragma unroll 8
;     for (int i = 0; i < 32; ++i) { const int kk = 2 * i + (lane >> 5); float w = __builtin_nontemporal_load(W + (size_t)(k0 + kk) * N + n0 + (lane & 31)); if (gain) w *= gain[k0 + kk]; scr[kk * 33 + (lane & 31)] = w; }
;     int d0 = n0;
;     if (mode == 1) { const int j = n0 < DFF ? n0 : n0 - DFF; d0 = 256 * (j >> 7) + (j & 127) + (n0 < DFF ? 0 : 128); }
;     const int c = lane & 7;
; #pragma unroll
;     for (int j = 0; j < 4; ++j) { const int n = (lane >> 3) + 8 * j; const LAS float* s = scr + (8 * c) * 33 + n;
;         u32x4 o; o.x = cvtpk(s[0 * 33], s[1 * 33]); o.y = cvtpk(s[2 * 33], s[3 * 33]); o.z = cvtpk(s[4 * 33], s[5 * 33]); o.w = cvtpk(s[6 * 33], s[7 * 33]);
;         *(u32x4*)(WT + (size_t)(d0 + n) * K + k0 + 8 * c) = o; }
.LBB0_357:
	v_lshl_add_u64 v[20:21], v[16:17], 0, s[2:3]
	v_lshl_add_u64 v[22:23], v[14:15], 0, s[2:3]
	v_lshl_add_u64 v[24:25], v[12:13], 0, s[2:3]
	v_lshl_add_u64 v[26:27], v[10:11], 0, s[2:3]
	v_lshl_add_u64 v[28:29], v[8:9], 0, s[2:3]
	v_lshl_add_u64 v[30:31], v[6:7], 0, s[2:3]
	v_lshl_add_u64 v[32:33], v[4:5], 0, s[2:3]
	s_waitcnt vmcnt(0)
	v_lshl_add_u64 v[34:35], v[2:3], 0, s[2:3]
	global_load_dword v100, v[20:21], off nt
	s_nop 0
	global_load_dword v101, v[22:23], off nt
	global_load_dword v102, v[24:25], off nt
	s_nop 0
	global_load_dword v103, v[26:27], off nt
	global_load_dword v104, v[28:29], off nt
	global_load_dword v105, v[30:31], off nt
	global_load_dword v106, v[32:33], off nt
	s_nop 0
	global_load_dword v107, v[34:35], off nt
	s_add_u32 s2, s2, 0x10000
	s_addc_u32 s3, s3, 0
	v_lshl_add_u64 v[20:21], v[16:17], 0, s[2:3]
	v_lshl_add_u64 v[22:23], v[14:15], 0, s[2:3]
	v_lshl_add_u64 v[24:25], v[12:13], 0, s[2:3]
	v_lshl_add_u64 v[26:27], v[10:11], 0, s[2:3]
	v_lshl_add_u64 v[28:29], v[8:9], 0, s[2:3]
	v_lshl_add_u64 v[30:31], v[6:7], 0, s[2:3]
	v_lshl_add_u64 v[32:33], v[4:5], 0, s[2:3]
	v_lshl_add_u64 v[34:35], v[2:3], 0, s[2:3]
	global_load_dword v116, v[20:21], off nt
	s_nop 0
	global_load_dword v117, v[22:23], off nt
	global_load_dword v118, v[24:25], off nt
	s_nop 0
	global_load_dword v119, v[26:27], off nt
	global_load_dword v120, v[28:29], off nt
	global_load_dword v121, v[30:31], off nt
	global_load_dword v122, v[32:33], off nt
	s_nop 0
	global_load_dword v123, v[34:35], off nt
	s_add_u32 s2, s2, 0x10000
	s_addc_u32 s3, s3, 0
	v_lshl_add_u64 v[20:21], v[16:17], 0, s[2:3]
	v_lshl_add_u64 v[22:23], v[14:15], 0, s[2:3]
	v_lshl_add_u64 v[24:25], v[12:13], 0, s[2:3]
	v_lshl_add_u64 v[26:27], v[10:11], 0, s[2:3]
	v_lshl_add_u64 v[28:29], v[8:9], 0, s[2:3]
	v_lshl_add_u64 v[30:31], v[6:7], 0, s[2:3]
	v_lshl_add_u64 v[32:33], v[4:5], 0, s[2:3]
	v_lshl_add_u64 v[34:35], v[2:3], 0, s[2:3]
	global_load_dword v132, v[20:21], off nt
	s_nop 0
	global_load_dword v133, v[22:23], off nt
	global_load_dword v134, v[24:25], off nt
	s_nop 0
	global_load_dword v135, v[26:27], off nt
	global_load_dword v136, v[28:29], off nt
	global_load_dword v137, v[30:31], off nt
	global_load_dword v138, v[32:33], off nt
	s_nop 0
	global_load_dword v139, v[34:35], off nt
	s_add_u32 s2, s2, 0x10000
	s_addc_u32 s3, s3, 0
	v_lshl_add_u64 v[20:21], v[16:17], 0, s[2:3]
	v_lshl_add_u64 v[22:23], v[14:15], 0, s[2:3]
	v_lshl_add_u64 v[24:25], v[12:13], 0, s[2:3]
	v_lshl_add_u64 v[26:27], v[10:11], 0, s[2:3]
	v_lshl_add_u64 v[28:29], v[8:9], 0, s[2:3]
	v_lshl_add_u64 v[30:31], v[6:7], 0, s[2:3]
	v_lshl_add_u64 v[32:33], v[4:5], 0, s[2:3]
	v_lshl_add_u64 v[34:35], v[2:3], 0, s[2:3]
	global_load_dword v148, v[20:21], off nt
	s_nop 0
	global_load_dword v149, v[22:23], off nt
	global_load_dword v150, v[24:25], off nt
	s_nop 0
	global_load_dword v151, v[26:27], off nt
	global_load_dword v152, v[28:29], off nt
	global_load_dword v153, v[30:31], off nt
	global_load_dword v154, v[32:33], off nt
	s_nop 0
	global_load_dword v155, v[34:35], off nt
	s_add_u32 s2, s2, 0x10000
	s_addc_u32 s3, s3, 0
	v_add_u32_e32 v27, 0x400, v19
	s_waitcnt vmcnt(30)
	ds_write2_b32 v19, v100, v101 offset1:66
	s_waitcnt vmcnt(28)
	ds_write2_b32 v19, v102, v103 offset0:132 offset1:198
	s_waitcnt vmcnt(26)
	ds_write2_b32 v27, v104, v105 offset0:8 offset1:74
	s_waitcnt vmcnt(24)
	ds_write2_b32 v27, v106, v107 offset0:140 offset1:206
	v_add_u32_e32 v19, 0x840, v19
	v_add_u32_e32 v27, 0x400, v19
	s_waitcnt vmcnt(22)
	ds_write2_b32 v19, v116, v117 offset1:66
	s_waitcnt vmcnt(20)
; #define LAS __attribute__((address_space(3)))
; __device__ __forceinline__ unsigned cvtpk(float lo, float hi) { f32x2 v = {lo, hi}; bf16x2_t b = __builtin_convertvector(v, bf16x2_t); return __builtin_bit_cast(unsigned, b); }
; __device__ __forceinline__ void transpose_item(const float* W, int K, int N, bf16_t* WT, const float* gain, int mode, LAS float* scr, int item, int lane) {
;     ...
;     for (int i = 0; i < 32; ++i) { const int kk = 2 * i + (lane >> 5); float w = __builtin_nontemporal_load(W + (size_t)(k0 + kk) * N + n0 + (lane & 31)); if (gain) w *= gain[k0 + kk]; scr[kk * 33 + (lane & 31)] = w; }
;     int d0 = n0;
;     if (mode == 1) { const int j = n0 < DFF ? n0 : n0 - DFF; d0 = 256 * (j >> 7) + (j & 127) + (n0 < DFF ? 0 : 128); }
;     const int c = lane & 7;
; #pragma unroll
;     for (int j = 0; j < 4; ++j) { const int n = (lane >> 3) + 8 * j; const LAS float* s = scr + (8 * c) * 33 + n;
;         u32x4 o; o.x = cvtpk(s[0 * 33], s[1 * 33]); o.y = cvtpk(s[2 * 33], s[3 * 33]); o.z = cvtpk(s[4 * 33], s[5 * 33]); o.w = cvtpk(s[6 * 33], s[7 * 33]);
;         *(u32x4*)(WT + (size_t)(d0 + n) * K + k0 + 8 * c) = o; }
	ds_write2_b32 v19, v118, v119 offset0:132 offset1:198
	s_waitcnt vmcnt(18)
	ds_write2_b32 v27, v120, v121 offset0:8 offset1:74
	s_waitcnt vmcnt(16)
	ds_write2_b32 v27, v122, v123 offset0:140 offset1:206
	v_add_u32_e32 v19, 0x840, v19
	v_add_u32_e32 v27, 0x400, v19
	s_waitcnt vmcnt(14)
	ds_write2_b32 v19, v132, v133 offset1:66
	s_waitcnt vmcnt(12)
	ds_write2_b32 v19, v134, v135 offset0:132 offset1:198
	s_waitcnt vmcnt(10)
	ds_write2_b32 v27, v136, v137 offset0:8 offset1:74
	s_waitcnt vmcnt(8)
	ds_write2_b32 v27, v138, v139 offset0:140 offset1:206
	v_add_u32_e32 v19, 0x840, v19
	v_add_u32_e32 v27, 0x400, v19
	s_waitcnt vmcnt(6)
	ds_write2_b32 v19, v148, v149 offset1:66
	s_waitcnt vmcnt(4)
	ds_write2_b32 v19, v150, v151 offset0:132 offset1:198
	s_waitcnt vmcnt(2)
	ds_write2_b32 v27, v152, v153 offset0:8 offset1:74
	s_waitcnt vmcnt(0)
	ds_write2_b32 v27, v154, v155 offset0:140 offset1:206
	v_add_u32_e32 v19, 0x840, v19
	v_lshlrev_b32_e32 v0, 3, v18
	v_ashrrev_i32_e32 v24, 3, v18
	v_and_b32_e32 v0, 56, v0
	s_lshl_b32 s2, s36, 1
	v_mul_u32_u24_e32 v2, 0x84, v0
	v_lshlrev_b32_e32 v3, 2, v24
	v_readlane_b32 s11, v254, 15
	s_add_i32 s2, s2, 0x1f700
	s_and_b32 s2, s2, 0x1ffc0
	v_add3_u32 v28, s11, v2, v3
	s_lshl_b32 s3, s36, 5
	ds_read2_b32 v[6:7], v28 offset0:33 offset1:41
	ds_read2_b32 v[8:9], v28 offset1:8
	ds_read2_b32 v[10:11], v28 offset0:66 offset1:74
	ds_read2_b32 v[12:13], v28 offset0:99 offset1:107
	ds_read2_b32 v[14:15], v28 offset0:132 offset1:140
	ds_read2_b32 v[16:17], v28 offset0:165 offset1:173
	ds_read2_b32 v[18:19], v28 offset0:198 offset1:206
	ds_read2_b32 v[20:21], v28 offset0:231 offset1:239
	s_and_b32 s10, s3, 0x3e0
	s_lshl_b32 s2, s2, 1
	s_add_u32 s2, s22, s2
	v_add_u32_e32 v24, s10, v24
	s_addc_u32 s3, s23, 0
	v_lshlrev_b32_e32 v0, 1, v0
	v_ashrrev_i32_e32 v25, 31, v24
	v_lshl_add_u64 v[22:23], s[2:3], 0, v[0:1]
	v_lshlrev_b64 v[26:27], 11, v[24:25]
	s_waitcnt lgkmcnt(6)
	v_cvt_pk_bf16_f32 v2, v8, v6
	s_waitcnt lgkmcnt(4)
	v_cvt_pk_bf16_f32 v3, v10, v12
	s_waitcnt lgkmcnt(2)
	v_cvt_pk_bf16_f32 v4, v14, v16
	s_waitcnt lgkmcnt(0)
	v_cvt_pk_bf16_f32 v5, v18, v20
	v_lshl_add_u64 v[26:27], v[22:23], 0, v[26:27]
	v_add_u32_e32 v6, 8, v24
	global_store_dwordx4 v[26:27], v[2:5], off
	s_nop 1
	v_cvt_pk_bf16_f32 v2, v9, v7
	v_ashrrev_i32_e32 v7, 31, v6
	v_cvt_pk_bf16_f32 v3, v11, v13
	v_cvt_pk_bf16_f32 v4, v15, v17
	v_cvt_pk_bf16_f32 v5, v19, v21
	v_lshlrev_b64 v[6:7], 11, v[6:7]
	ds_read2_b32 v[8:9], v28 offset0:49 offset1:57
	ds_read2_b32 v[10:11], v28 offset0:16 offset1:24
	ds_read2_b32 v[12:13], v28 offset0:82 offset1:90
	ds_read2_b32 v[14:15], v28 offset0:115 offset1:123
	ds_read2_b32 v[16:17], v28 offset0:148 offset1:156
	ds_read2_b32 v[18:19], v28 offset0:181 offset1:189
	ds_read2_b32 v[20:21], v28 offset0:214 offset1:222
	ds_read2_b32 v[26:27], v28 offset0:247 offset1:255
	v_lshl_add_u64 v[6:7], v[22:23], 0, v[6:7]
	global_store_dwordx4 v[6:7], v[2:5], off
	v_add_u32_e32 v6, 16, v24
	v_ashrrev_i32_e32 v7, 31, v6
	v_lshlrev_b64 v[6:7], 11, v[6:7]
	s_waitcnt lgkmcnt(6)
	v_cvt_pk_bf16_f32 v2, v10, v8
	s_waitcnt lgkmcnt(4)
	v_cvt_pk_bf16_f32 v3, v12, v14
	s_waitcnt lgkmcnt(2)
	v_cvt_pk_bf16_f32 v4, v16, v18
	s_waitcnt lgkmcnt(0)
	v_cvt_pk_bf16_f32 v5, v20, v26
	v_lshl_add_u64 v[6:7], v[22:23], 0, v[6:7]
	global_store_dwordx4 v[6:7], v[2:5], off
	v_add_u32_e32 v6, 24, v24
	v_ashrrev_i32_e32 v7, 31, v6
	v_lshlrev_b64 v[6:7], 11, v[6:7]
	v_cvt_pk_bf16_f32 v2, v11, v9
	v_cvt_pk_bf16_f32 v3, v13, v15
	v_cvt_pk_bf16_f32 v4, v17, v19
	v_cvt_pk_bf16_f32 v5, v21, v27
	v_lshl_add_u64 v[6:7], v[22:23], 0, v[6:7]
	global_store_dwordx4 v[6:7], v[2:5], off
